# on top: redundant lgkmcnt(0) after the pre-MFMA barrier removed
# speedup vs baseline: 1.0089x; 1.0089x over previous
; #define PG8_STAGE(bufoff, gbase, voff) do { _Pragma("unroll") for (int _i = 0; _i < 2; ++_i) \
;         __builtin_amdgcn_global_load_lds((const unsigned*)((const char*)(gbase) + (voff)[_i]), (PG8_LAS unsigned*)(lds + (bufoff) + ldsw + _i * 8192), 16, 0, 0); } while (0)
; #define PG8_LDA(dst, b, h) do { _Pragma("unroll") for (int m = 0; m < 4; ++m) _Pragma("unroll") for (int k = 0; k < 2; ++k) dst[m][k] = *(const PG8_LAS bf16x8*)(lds + PG8_SA(b, h) + aoff + m * 2048 + k * 1024); } while (0)
; #define PG8_LDB(dst, b, h) do { _Pragma("unroll") for (int n = 0; n < 2; ++n) _Pragma("unroll") for (int k = 0; k < 2; ++k) dst[n][k] = *(const PG8_LAS bf16x8*)(lds + PG8_SB(b, h) + boff + n * 2048 + k * 1024); } while (0)
; #define PG8_WAIT_V(n) asm volatile("s_waitcnt vmcnt(" #n ")" ::: "memory")
; #define PG8_WAIT_L(n) asm volatile("s_waitcnt lgkmcnt(" #n ")" ::: "memory")
; #define PG8_BAR __builtin_amdgcn_s_barrier()
; #define PG8_SCHED __builtin_amdgcn_sched_barrier(0)
; template <class Epi, class Sched, bool ALIGN_EPI = false, bool SP2 = false>
; __device__ __forceinline__ void gemm_phase(PG8_LAS unsigned char* lds, const Gemm g, const Sched& S, const Epi& E) {
;     ...
;         const bool has_next = S.next(ui + 1, nxt);
;         const char* nA = has_next ? (const char*)g.A + (size_t)nxt.pm * tstep : cA; const char* nB = has_next ? (const char*)g.Bt + (size_t)nxt.pn * tstep : cB;
;         for (int t = 0; t < nt; t += 2) {
;             const bool last = (t == nt - 2);
;             const char* a1 = cA + (size_t)(t + 1) * kstep;
;             const char* a2 = last ? nA : cA + (size_t)(t + 2) * kstep; const char* b2 = last ? nB : cB + (size_t)(t + 2) * kstep;
;             const char* a3 = a2 + kstep; const char* b3 = b2 + kstep;
;             if (last && has_next) S.a_ready(nxt);
;             if constexpr (SP2) {
;             PG8_LDB(B0, 0, 0); PG8_LDB(B1, 0, 1); PG8_SCHED; PG8_LDA(At, 0, 0); PG8_STAGE(PG8_SA(1, 1), a1 + hstep, voffA);
;             PG8_WAIT_V(8); PG8_WAIT_L(0); PG8_BAR; PG8_MMA(0, 0, At, B0); PG8_MMA(0, 1, At, B1); PG8_BAR; PG8_SCHED;
;             PG8_LDA(At, 0, 1); PG8_STAGE(PG8_SB(0, 0), b2, voffB); PG8_STAGE(PG8_SB(0, 1), b2 + hstep, voffB); PG8_STAGE(PG8_SA(0, 0), a2, voffA);
;             PG8_WAIT_V(8); PG8_WAIT_L(0); PG8_BAR; PG8_MMA(1, 0, At, B0); PG8_MMA(1, 1, At, B1); PG8_BAR; PG8_SCHED;
.LBB0_132:
	s_add_u32 s18, s46, 0xfffc0080
	s_addc_u32 s38, s47, -1
	s_add_i32 s39, 0, 0x10000
	s_cmp_eq_u32 s85, 12
	s_cselect_b32 s81, s33, s38
	s_cselect_b32 s80, s73, s18
	v_add_u32_e32 v0, s39, v176
	s_cselect_b32 s45, s75, s84
	s_cselect_b32 s44, s82, s83
	s_add_i32 s18, 0, 0x14000
	ds_read_b128 v[144:147], v0
	ds_read_b128 v[148:151], v0 offset:1024
	ds_read_b128 v[152:155], v0 offset:2048
	ds_read_b128 v[156:159], v0 offset:3072
	v_add_u32_e32 v0, s18, v176
	ds_read_b128 v[160:163], v0
	ds_read_b128 v[164:167], v0 offset:1024
	ds_read_b128 v[168:171], v0 offset:2048
	ds_read_b128 v[172:175], v0 offset:3072
	v_lshl_add_u64 v[218:219], s[46:47], 0, v[140:141]
	s_add_i32 m0, s92, 0xc000
	ds_read_b128 v[180:183], v178
	ds_read_b128 v[184:187], v178 offset:1024
	ds_read_b128 v[188:191], v178 offset:2048
	ds_read_b128 v[192:195], v178 offset:3072
	ds_read_b128 v[202:205], v178 offset:4096
	ds_read_b128 v[206:209], v178 offset:5120
	ds_read_b128 v[210:213], v178 offset:6144
	ds_read_b128 v[214:217], v178 offset:7168
	global_load_lds_dwordx4 v[218:219], off
	v_lshl_add_u64 v[218:219], s[46:47], 0, v[142:143]
	s_add_i32 m0, s92, 0xe000
	s_nop 0
	global_load_lds_dwordx4 v[218:219], off
	s_waitcnt vmcnt(8)
	s_waitcnt lgkmcnt(0)
	s_barrier
	s_setprio 1
	v_mfma_f32_16x16x32_bf16 v[118:121], v[144:147], v[180:183], v[118:121]
	v_mfma_f32_16x16x32_bf16 v[118:121], v[148:151], v[184:187], v[118:121]
	v_mfma_f32_16x16x32_bf16 v[102:105], v[144:147], v[188:191], v[102:105]
	v_mfma_f32_16x16x32_bf16 v[102:105], v[148:151], v[192:195], v[102:105]
	v_mfma_f32_16x16x32_bf16 v[86:89], v[144:147], v[202:205], v[86:89]
	v_mfma_f32_16x16x32_bf16 v[86:89], v[148:151], v[206:209], v[86:89]
	v_mfma_f32_16x16x32_bf16 v[70:73], v[144:147], v[210:213], v[70:73]
	v_mfma_f32_16x16x32_bf16 v[70:73], v[148:151], v[214:217], v[70:73]
	v_mfma_f32_16x16x32_bf16 v[114:117], v[152:155], v[180:183], v[114:117]
	v_mfma_f32_16x16x32_bf16 v[114:117], v[156:159], v[184:187], v[114:117]
	v_mfma_f32_16x16x32_bf16 v[98:101], v[152:155], v[188:191], v[98:101]
	v_mfma_f32_16x16x32_bf16 v[98:101], v[156:159], v[192:195], v[98:101]
	v_mfma_f32_16x16x32_bf16 v[82:85], v[152:155], v[202:205], v[82:85]
	v_mfma_f32_16x16x32_bf16 v[82:85], v[156:159], v[206:209], v[82:85]
	v_mfma_f32_16x16x32_bf16 v[66:69], v[152:155], v[210:213], v[66:69]
	v_mfma_f32_16x16x32_bf16 v[66:69], v[156:159], v[214:217], v[66:69]
	v_mfma_f32_16x16x32_bf16 v[126:129], v[160:163], v[180:183], v[126:129]
	v_mfma_f32_16x16x32_bf16 v[126:129], v[164:167], v[184:187], v[126:129]
	v_mfma_f32_16x16x32_bf16 v[110:113], v[160:163], v[188:191], v[110:113]
	v_mfma_f32_16x16x32_bf16 v[110:113], v[164:167], v[192:195], v[110:113]
	v_mfma_f32_16x16x32_bf16 v[94:97], v[160:163], v[202:205], v[94:97]
	v_mfma_f32_16x16x32_bf16 v[94:97], v[164:167], v[206:209], v[94:97]
	v_mfma_f32_16x16x32_bf16 v[78:81], v[160:163], v[210:213], v[78:81]
	v_mfma_f32_16x16x32_bf16 v[78:81], v[164:167], v[214:217], v[78:81]
	v_mfma_f32_16x16x32_bf16 v[122:125], v[168:171], v[180:183], v[122:125]
	v_mfma_f32_16x16x32_bf16 v[122:125], v[172:175], v[184:187], v[122:125]
	v_mfma_f32_16x16x32_bf16 v[106:109], v[168:171], v[188:191], v[106:109]
	v_mfma_f32_16x16x32_bf16 v[106:109], v[172:175], v[192:195], v[106:109]
	v_mfma_f32_16x16x32_bf16 v[90:93], v[168:171], v[202:205], v[90:93]
	v_mfma_f32_16x16x32_bf16 v[90:93], v[172:175], v[206:209], v[90:93]
	v_mfma_f32_16x16x32_bf16 v[74:77], v[168:171], v[210:213], v[74:77]
	v_mfma_f32_16x16x32_bf16 v[74:77], v[172:175], v[214:217], v[74:77]
	s_setprio 0
	s_barrier
	s_add_i32 s38, s39, s91
	v_lshl_add_u64 v[218:219], s[44:45], 0, v[134:135]
	s_mov_b32 m0, s38
	ds_read_b128 v[180:183], v178 offset:16384
	ds_read_b128 v[184:187], v178 offset:17408
	ds_read_b128 v[188:191], v178 offset:18432
	ds_read_b128 v[192:195], v178 offset:19456
	ds_read_b128 v[202:205], v178 offset:20480
	ds_read_b128 v[206:209], v178 offset:21504
	ds_read_b128 v[210:213], v178 offset:22528
	ds_read_b128 v[214:217], v178 offset:23552
	global_load_lds_dwordx4 v[218:219], off
	s_add_i32 m0, s38, 0x2000
	s_add_u32 s38, s44, 0x40000
	v_lshl_add_u64 v[220:221], s[44:45], 0, v[130:131]
	s_addc_u32 s39, s45, 0
	s_add_i32 s18, s18, s91
	global_load_lds_dwordx4 v[220:221], off
	v_lshl_add_u64 v[222:223], s[38:39], 0, v[134:135]
	s_mov_b32 m0, s18
	v_lshl_add_u64 v[224:225], s[80:81], 0, v[132:133]
	global_load_lds_dwordx4 v[222:223], off
	v_lshl_add_u64 v[222:223], s[38:39], 0, v[130:131]
	s_add_i32 m0, s18, 0x2000
	s_nop 0
	global_load_lds_dwordx4 v[222:223], off
	v_lshl_add_u64 v[222:223], s[80:81], 0, v[136:137]
	s_mov_b32 m0, s92
	s_nop 0
	global_load_lds_dwordx4 v[222:223], off
	s_mov_b32 m0, s93
	s_nop 0
	global_load_lds_dwordx4 v[224:225], off
	s_waitcnt vmcnt(8)
	s_waitcnt lgkmcnt(0)
	s_barrier
; #define PG8_STAGE(bufoff, gbase, voff) do { _Pragma("unroll") for (int _i = 0; _i < 2; ++_i) \
;         __builtin_amdgcn_global_load_lds((const unsigned*)((const char*)(gbase) + (voff)[_i]), (PG8_LAS unsigned*)(lds + (bufoff) + ldsw + _i * 8192), 16, 0, 0); } while (0)
; #define PG8_LDA(dst, b, h) do { _Pragma("unroll") for (int m = 0; m < 4; ++m) _Pragma("unroll") for (int k = 0; k < 2; ++k) dst[m][k] = *(const PG8_LAS bf16x8*)(lds + PG8_SA(b, h) + aoff + m * 2048 + k * 1024); } while (0)
; #define PG8_LDB(dst, b, h) do { _Pragma("unroll") for (int n = 0; n < 2; ++n) _Pragma("unroll") for (int k = 0; k < 2; ++k) dst[n][k] = *(const PG8_LAS bf16x8*)(lds + PG8_SB(b, h) + boff + n * 2048 + k * 1024); } while (0)
; #define PG8_MMA(ai, bj, At, Bt) do { __builtin_amdgcn_s_setprio(1); _Pragma("unroll") for (int m = 0; m < 4; ++m) _Pragma("unroll") for (int n = 0; n < 2; ++n) _Pragma("unroll") for (int k = 0; k < 2; ++k) \
;         acc[ai][bj][m][n] = __builtin_amdgcn_mfma_f32_16x16x32_bf16(Bt[n][k], At[m][k], acc[ai][bj][m][n], 0, 0, 0); __builtin_amdgcn_s_setprio(0); } while (0)
; #define PG8_WAIT_V(n) asm volatile("s_waitcnt vmcnt(" #n ")" ::: "memory")
; #define PG8_WAIT_L(n) asm volatile("s_waitcnt lgkmcnt(" #n ")" ::: "memory")
; #define PG8_BAR __builtin_amdgcn_s_barrier()
; #define PG8_SCHED __builtin_amdgcn_sched_barrier(0)
; template <class Epi, class Sched, bool ALIGN_EPI = false, bool SP2 = false>
; __device__ __forceinline__ void gemm_phase(PG8_LAS unsigned char* lds, const Gemm g, const Sched& S, const Epi& E) {
;     ...
;             PG8_WAIT_V(8); PG8_WAIT_L(0); PG8_BAR; PG8_MMA(1, 0, At, B0); PG8_MMA(1, 1, At, B1); PG8_BAR; PG8_SCHED;
;             PG8_LDB(B0, 1, 0); PG8_LDB(B1, 1, 1); PG8_SCHED; PG8_LDA(At, 1, 0); PG8_STAGE(PG8_SA(0, 1), a2 + hstep, voffA);
;             PG8_WAIT_V(8); PG8_WAIT_L(0); PG8_BAR; PG8_MMA(0, 0, At, B0); PG8_MMA(0, 1, At, B1); PG8_BAR; PG8_SCHED;
	s_setprio 1
	v_mfma_f32_16x16x32_bf16 v[54:57], v[144:147], v[180:183], v[54:57]
	v_mfma_f32_16x16x32_bf16 v[54:57], v[148:151], v[184:187], v[54:57]
	v_mfma_f32_16x16x32_bf16 v[38:41], v[144:147], v[188:191], v[38:41]
	v_mfma_f32_16x16x32_bf16 v[38:41], v[148:151], v[192:195], v[38:41]
	v_mfma_f32_16x16x32_bf16 v[22:25], v[144:147], v[202:205], v[22:25]
	v_mfma_f32_16x16x32_bf16 v[22:25], v[148:151], v[206:209], v[22:25]
	v_mfma_f32_16x16x32_bf16 v[6:9], v[144:147], v[210:213], v[6:9]
	v_mfma_f32_16x16x32_bf16 v[6:9], v[148:151], v[214:217], v[6:9]
	v_mfma_f32_16x16x32_bf16 v[50:53], v[152:155], v[180:183], v[50:53]
	v_mfma_f32_16x16x32_bf16 v[50:53], v[156:159], v[184:187], v[50:53]
	v_mfma_f32_16x16x32_bf16 v[34:37], v[152:155], v[188:191], v[34:37]
	v_mfma_f32_16x16x32_bf16 v[34:37], v[156:159], v[192:195], v[34:37]
	v_mfma_f32_16x16x32_bf16 v[18:21], v[152:155], v[202:205], v[18:21]
	v_mfma_f32_16x16x32_bf16 v[18:21], v[156:159], v[206:209], v[18:21]
	v_mfma_f32_16x16x32_bf16 v[2:5], v[152:155], v[210:213], v[2:5]
	v_mfma_f32_16x16x32_bf16 v[2:5], v[156:159], v[214:217], v[2:5]
	v_mfma_f32_16x16x32_bf16 v[62:65], v[160:163], v[180:183], v[62:65]
	v_mfma_f32_16x16x32_bf16 v[62:65], v[164:167], v[184:187], v[62:65]
	v_mfma_f32_16x16x32_bf16 v[46:49], v[160:163], v[188:191], v[46:49]
	v_mfma_f32_16x16x32_bf16 v[46:49], v[164:167], v[192:195], v[46:49]
	v_mfma_f32_16x16x32_bf16 v[30:33], v[160:163], v[202:205], v[30:33]
	v_mfma_f32_16x16x32_bf16 v[30:33], v[164:167], v[206:209], v[30:33]
	v_mfma_f32_16x16x32_bf16 v[10:13], v[160:163], v[210:213], v[10:13]
	v_mfma_f32_16x16x32_bf16 v[10:13], v[164:167], v[214:217], v[10:13]
	v_mfma_f32_16x16x32_bf16 v[58:61], v[168:171], v[180:183], v[58:61]
	v_mfma_f32_16x16x32_bf16 v[58:61], v[172:175], v[184:187], v[58:61]
	v_mfma_f32_16x16x32_bf16 v[42:45], v[168:171], v[188:191], v[42:45]
	v_mfma_f32_16x16x32_bf16 v[42:45], v[172:175], v[192:195], v[42:45]
	v_mfma_f32_16x16x32_bf16 v[26:29], v[168:171], v[202:205], v[26:29]
	v_mfma_f32_16x16x32_bf16 v[26:29], v[172:175], v[206:209], v[26:29]
	v_mfma_f32_16x16x32_bf16 v[14:17], v[168:171], v[210:213], v[14:17]
	v_mfma_f32_16x16x32_bf16 v[14:17], v[172:175], v[214:217], v[14:17]
	s_setprio 0
	s_barrier
	s_add_i32 s18, 0, 0x18000
	v_add_u32_e32 v0, s18, v176
	s_add_i32 vcc_lo, 0, 0x1c000
	ds_read_b128 v[144:147], v0
	ds_read_b128 v[148:151], v0 offset:1024
	ds_read_b128 v[152:155], v0 offset:2048
	ds_read_b128 v[156:159], v0 offset:3072
	v_add_u32_e32 v0, vcc_lo, v176
	ds_read_b128 v[160:163], v0
	ds_read_b128 v[164:167], v0 offset:1024
	ds_read_b128 v[168:171], v0 offset:2048
	ds_read_b128 v[172:175], v0 offset:3072
	s_add_u32 s38, s80, 0x40000
	s_addc_u32 s39, s81, 0
	s_mov_b32 m0, s94
	v_lshl_add_u64 v[226:227], s[38:39], 0, v[136:137]
	ds_read_b128 v[180:183], v178 offset:32768
	ds_read_b128 v[184:187], v178 offset:33792
	ds_read_b128 v[188:191], v178 offset:34816
	ds_read_b128 v[192:195], v178 offset:35840
	ds_read_b128 v[202:205], v178 offset:36864
	ds_read_b128 v[206:209], v178 offset:37888
	ds_read_b128 v[210:213], v178 offset:38912
	ds_read_b128 v[214:217], v178 offset:39936
	global_load_lds_dwordx4 v[226:227], off
	v_lshl_add_u64 v[226:227], s[38:39], 0, v[132:133]
	s_mov_b32 m0, s95
	s_nop 0
	global_load_lds_dwordx4 v[226:227], off
	s_waitcnt vmcnt(8)
	s_waitcnt lgkmcnt(0)
	s_barrier
	s_setprio 1
	v_mfma_f32_16x16x32_bf16 v[118:121], v[144:147], v[180:183], v[118:121]
	v_mfma_f32_16x16x32_bf16 v[118:121], v[148:151], v[184:187], v[118:121]
	v_mfma_f32_16x16x32_bf16 v[102:105], v[144:147], v[188:191], v[102:105]
	v_mfma_f32_16x16x32_bf16 v[102:105], v[148:151], v[192:195], v[102:105]
	v_mfma_f32_16x16x32_bf16 v[86:89], v[144:147], v[202:205], v[86:89]
	v_mfma_f32_16x16x32_bf16 v[86:89], v[148:151], v[206:209], v[86:89]
	v_mfma_f32_16x16x32_bf16 v[70:73], v[144:147], v[210:213], v[70:73]
	v_mfma_f32_16x16x32_bf16 v[70:73], v[148:151], v[214:217], v[70:73]
	v_mfma_f32_16x16x32_bf16 v[114:117], v[152:155], v[180:183], v[114:117]
	v_mfma_f32_16x16x32_bf16 v[114:117], v[156:159], v[184:187], v[114:117]
	v_mfma_f32_16x16x32_bf16 v[98:101], v[152:155], v[188:191], v[98:101]
	v_mfma_f32_16x16x32_bf16 v[98:101], v[156:159], v[192:195], v[98:101]
	v_mfma_f32_16x16x32_bf16 v[82:85], v[152:155], v[202:205], v[82:85]
	v_mfma_f32_16x16x32_bf16 v[82:85], v[156:159], v[206:209], v[82:85]
	v_mfma_f32_16x16x32_bf16 v[66:69], v[152:155], v[210:213], v[66:69]
	v_mfma_f32_16x16x32_bf16 v[66:69], v[156:159], v[214:217], v[66:69]
	v_mfma_f32_16x16x32_bf16 v[126:129], v[160:163], v[180:183], v[126:129]
	v_mfma_f32_16x16x32_bf16 v[126:129], v[164:167], v[184:187], v[126:129]
	v_mfma_f32_16x16x32_bf16 v[110:113], v[160:163], v[188:191], v[110:113]
	v_mfma_f32_16x16x32_bf16 v[110:113], v[164:167], v[192:195], v[110:113]
	v_mfma_f32_16x16x32_bf16 v[94:97], v[160:163], v[202:205], v[94:97]
	v_mfma_f32_16x16x32_bf16 v[94:97], v[164:167], v[206:209], v[94:97]
	v_mfma_f32_16x16x32_bf16 v[78:81], v[160:163], v[210:213], v[78:81]
	v_mfma_f32_16x16x32_bf16 v[78:81], v[164:167], v[214:217], v[78:81]
	v_mfma_f32_16x16x32_bf16 v[122:125], v[168:171], v[180:183], v[122:125]
	v_mfma_f32_16x16x32_bf16 v[122:125], v[172:175], v[184:187], v[122:125]
	v_mfma_f32_16x16x32_bf16 v[106:109], v[168:171], v[188:191], v[106:109]
	v_mfma_f32_16x16x32_bf16 v[106:109], v[172:175], v[192:195], v[106:109]
	v_mfma_f32_16x16x32_bf16 v[90:93], v[168:171], v[202:205], v[90:93]
	v_mfma_f32_16x16x32_bf16 v[90:93], v[172:175], v[206:209], v[90:93]
	v_mfma_f32_16x16x32_bf16 v[74:77], v[168:171], v[210:213], v[74:77]
	v_mfma_f32_16x16x32_bf16 v[74:77], v[172:175], v[214:217], v[74:77]
	s_setprio 0
	s_barrier
; #define PG8_STAGE(bufoff, gbase, voff) do { _Pragma("unroll") for (int _i = 0; _i < 2; ++_i) \
;         __builtin_amdgcn_global_load_lds((const unsigned*)((const char*)(gbase) + (voff)[_i]), (PG8_LAS unsigned*)(lds + (bufoff) + ldsw + _i * 8192), 16, 0, 0); } while (0)
; #define PG8_LDA(dst, b, h) do { _Pragma("unroll") for (int m = 0; m < 4; ++m) _Pragma("unroll") for (int k = 0; k < 2; ++k) dst[m][k] = *(const PG8_LAS bf16x8*)(lds + PG8_SA(b, h) + aoff + m * 2048 + k * 1024); } while (0)
; #define PG8_WAIT_V(n) asm volatile("s_waitcnt vmcnt(" #n ")" ::: "memory")
; template <class Epi, class Sched, bool ALIGN_EPI = false, bool SP2 = false>
; __device__ __forceinline__ void gemm_phase(PG8_LAS unsigned char* lds, const Gemm g, const Sched& S, const Epi& E) {
;     ...
;             PG8_LDA(At, 1, 1); PG8_STAGE(PG8_SB(1, 0), b3, voffB); PG8_STAGE(PG8_SB(1, 1), b3 + hstep, voffB); PG8_STAGE(PG8_SA(1, 0), a3, voffA);
;             PG8_WAIT_V(8); PG8_WAIT_L(0); PG8_BAR; PG8_MMA(1, 0, At, B0); PG8_MMA(1, 1, At, B1); PG8_BAR; PG8_SCHED;
;             } else {
;             PG8_LDB(B0, 0, 0); PG8_SCHED; PG8_LDA(At, 0, 0); PG8_STAGE(PG8_SA(1, 1), a1 + hstep, voffA);
;             PG8_WAIT_L(8); PG8_BAR; PG8_WAIT_L(0); PG8_MMA(0, 0, At, B0); PG8_BAR; PG8_SCHED;
;             PG8_LDB(B1, 0, 1); PG8_STAGE(PG8_SB(0, 0), b2, voffB);
;             PG8_BAR; PG8_WAIT_L(0); PG8_MMA(0, 1, At, B1); PG8_BAR;
;             PG8_LDA(At, 0, 1); PG8_STAGE(PG8_SA(0, 0), a2, voffA);
;             PG8_BAR; PG8_WAIT_L(0); PG8_MMA(1, 0, At, B0); PG8_BAR; PG8_SCHED;
;             PG8_STAGE(PG8_SB(0, 1), b2 + hstep, voffB);
;             PG8_WAIT_V(6); PG8_BAR; PG8_MMA(1, 1, At, B1); PG8_BAR;
;             PG8_LDB(B0, 1, 0); PG8_SCHED; PG8_LDA(At, 1, 0); PG8_STAGE(PG8_SA(0, 1), a2 + hstep, voffA);
;             PG8_WAIT_L(8); PG8_BAR; PG8_WAIT_L(0); PG8_MMA(0, 0, At, B0); PG8_BAR; PG8_SCHED;
;             PG8_LDB(B1, 1, 1); PG8_STAGE(PG8_SB(1, 0), b3, voffB);
;             PG8_BAR; PG8_WAIT_L(0); PG8_MMA(0, 1, At, B1); PG8_BAR;
;             PG8_LDA(At, 1, 1); PG8_STAGE(PG8_SA(1, 0), a3, voffA);
;             PG8_BAR; PG8_WAIT_L(0); PG8_MMA(1, 0, At, B0); PG8_BAR; PG8_SCHED;
;             PG8_STAGE(PG8_SB(1, 1), b3 + hstep, voffB);
;             PG8_WAIT_V(6); PG8_BAR; PG8_MMA(1, 1, At, B1); PG8_BAR;
;             }
;         }
;         if constexpr (ALIGN_EPI) { if (wr == 0) PG8_BAR; }
	s_add_i32 s18, s18, s91
	v_lshl_add_u64 v[218:219], v[218:219], 0, s[30:31]
	s_mov_b32 m0, s18
	ds_read_b128 v[180:183], v178 offset:49152
	ds_read_b128 v[184:187], v178 offset:50176
	ds_read_b128 v[188:191], v178 offset:51200
	ds_read_b128 v[192:195], v178 offset:52224
	ds_read_b128 v[202:205], v178 offset:53248
	ds_read_b128 v[206:209], v178 offset:54272
	ds_read_b128 v[210:213], v178 offset:55296
	ds_read_b128 v[214:217], v178 offset:56320
	global_load_lds_dwordx4 v[218:219], off
	s_add_i32 m0, s18, 0x2000
	s_add_u32 s38, s44, 0x40080
	v_lshl_add_u64 v[218:219], v[220:221], 0, s[30:31]
	s_addc_u32 s39, s45, 0
	s_add_i32 s18, vcc_lo, s91
	global_load_lds_dwordx4 v[218:219], off
	v_lshl_add_u64 v[218:219], s[38:39], 0, v[134:135]
	s_mov_b32 m0, s18
	s_nop 0
	global_load_lds_dwordx4 v[218:219], off
	v_lshl_add_u64 v[218:219], s[38:39], 0, v[130:131]
	s_add_i32 m0, s18, 0x2000
	s_nop 0
	global_load_lds_dwordx4 v[218:219], off
	v_lshl_add_u64 v[218:219], v[222:223], 0, s[30:31]
	s_mov_b32 m0, s7
	s_nop 0
	global_load_lds_dwordx4 v[218:219], off
	v_lshl_add_u64 v[218:219], v[224:225], 0, s[30:31]
	s_mov_b32 m0, s96
	s_nop 0
	global_load_lds_dwordx4 v[218:219], off
	s_waitcnt vmcnt(8)
	s_waitcnt lgkmcnt(0)
	s_barrier
	s_setprio 1
	v_mfma_f32_16x16x32_bf16 v[54:57], v[144:147], v[180:183], v[54:57]
	v_mfma_f32_16x16x32_bf16 v[54:57], v[148:151], v[184:187], v[54:57]
	v_mfma_f32_16x16x32_bf16 v[38:41], v[144:147], v[188:191], v[38:41]
	v_mfma_f32_16x16x32_bf16 v[38:41], v[148:151], v[192:195], v[38:41]
	v_mfma_f32_16x16x32_bf16 v[22:25], v[144:147], v[202:205], v[22:25]
	v_mfma_f32_16x16x32_bf16 v[22:25], v[148:151], v[206:209], v[22:25]
	v_mfma_f32_16x16x32_bf16 v[6:9], v[144:147], v[210:213], v[6:9]
	v_mfma_f32_16x16x32_bf16 v[6:9], v[148:151], v[214:217], v[6:9]
	v_mfma_f32_16x16x32_bf16 v[50:53], v[152:155], v[180:183], v[50:53]
	v_mfma_f32_16x16x32_bf16 v[50:53], v[156:159], v[184:187], v[50:53]
	v_mfma_f32_16x16x32_bf16 v[34:37], v[152:155], v[188:191], v[34:37]
	v_mfma_f32_16x16x32_bf16 v[34:37], v[156:159], v[192:195], v[34:37]
	v_mfma_f32_16x16x32_bf16 v[18:21], v[152:155], v[202:205], v[18:21]
	v_mfma_f32_16x16x32_bf16 v[18:21], v[156:159], v[206:209], v[18:21]
	v_mfma_f32_16x16x32_bf16 v[2:5], v[152:155], v[210:213], v[2:5]
	v_mfma_f32_16x16x32_bf16 v[2:5], v[156:159], v[214:217], v[2:5]
	v_mfma_f32_16x16x32_bf16 v[62:65], v[160:163], v[180:183], v[62:65]
	v_mfma_f32_16x16x32_bf16 v[62:65], v[164:167], v[184:187], v[62:65]
	v_mfma_f32_16x16x32_bf16 v[46:49], v[160:163], v[188:191], v[46:49]
	v_mfma_f32_16x16x32_bf16 v[46:49], v[164:167], v[192:195], v[46:49]
	v_mfma_f32_16x16x32_bf16 v[30:33], v[160:163], v[202:205], v[30:33]
	v_mfma_f32_16x16x32_bf16 v[30:33], v[164:167], v[206:209], v[30:33]
	v_mfma_f32_16x16x32_bf16 v[10:13], v[160:163], v[210:213], v[10:13]
	v_mfma_f32_16x16x32_bf16 v[10:13], v[164:167], v[214:217], v[10:13]
	v_mfma_f32_16x16x32_bf16 v[58:61], v[168:171], v[180:183], v[58:61]
	v_mfma_f32_16x16x32_bf16 v[58:61], v[172:175], v[184:187], v[58:61]
	v_mfma_f32_16x16x32_bf16 v[42:45], v[168:171], v[188:191], v[42:45]
	v_mfma_f32_16x16x32_bf16 v[42:45], v[172:175], v[192:195], v[42:45]
	v_mfma_f32_16x16x32_bf16 v[26:29], v[168:171], v[202:205], v[26:29]
	v_mfma_f32_16x16x32_bf16 v[26:29], v[172:175], v[206:209], v[26:29]
	v_mfma_f32_16x16x32_bf16 v[14:17], v[168:171], v[210:213], v[14:17]
	v_mfma_f32_16x16x32_bf16 v[14:17], v[172:175], v[214:217], v[14:17]
	s_setprio 0
	s_barrier
	s_add_i32 s85, s85, 2
	s_add_u32 s46, s46, 0x100
	s_addc_u32 s47, s47, 0
	s_add_u32 s83, s83, 0x100
	s_addc_u32 s84, s84, 0
	s_cmp_gt_u32 s85, 13
	s_cbranch_scc0 .LBB0_132
	s_and_b64 vcc, exec, s[10:11]
	s_cbranch_vccz .LBB0_135
	s_barrier

; #define PG8_STAGE(bufoff, gbase, voff) do { _Pragma("unroll") for (int _i = 0; _i < 2; ++_i) \
;         __builtin_amdgcn_global_load_lds((const unsigned*)((const char*)(gbase) + (voff)[_i]), (PG8_LAS unsigned*)(lds + (bufoff) + ldsw + _i * 8192), 16, 0, 0); } while (0)
; #define PG8_LDA(dst, b, h) do { _Pragma("unroll") for (int m = 0; m < 4; ++m) _Pragma("unroll") for (int k = 0; k < 2; ++k) dst[m][k] = *(const PG8_LAS bf16x8*)(lds + PG8_SA(b, h) + aoff + m * 2048 + k * 1024); } while (0)
; #define PG8_LDB(dst, b, h) do { _Pragma("unroll") for (int n = 0; n < 2; ++n) _Pragma("unroll") for (int k = 0; k < 2; ++k) dst[n][k] = *(const PG8_LAS bf16x8*)(lds + PG8_SB(b, h) + boff + n * 2048 + k * 1024); } while (0)
; #define PG8_WAIT_V(n) asm volatile("s_waitcnt vmcnt(" #n ")" ::: "memory")
; #define PG8_WAIT_L(n) asm volatile("s_waitcnt lgkmcnt(" #n ")" ::: "memory")
; #define PG8_BAR __builtin_amdgcn_s_barrier()
; #define PG8_SCHED __builtin_amdgcn_sched_barrier(0)
; template <class Epi, class Sched, bool ALIGN_EPI = false, bool SP2 = false>
; __device__ __forceinline__ void gemm_phase(PG8_LAS unsigned char* lds, const Gemm g, const Sched& S, const Epi& E) {
;     ...
;         const bool has_next = S.next(ui + 1, nxt);
;         const char* nA = has_next ? (const char*)g.A + (size_t)nxt.pm * tstep : cA; const char* nB = has_next ? (const char*)g.Bt + (size_t)nxt.pn * tstep : cB;
;         for (int t = 0; t < nt; t += 2) {
;             const bool last = (t == nt - 2);
;             const char* a1 = cA + (size_t)(t + 1) * kstep;
;             const char* a2 = last ? nA : cA + (size_t)(t + 2) * kstep; const char* b2 = last ? nB : cB + (size_t)(t + 2) * kstep;
;             const char* a3 = a2 + kstep; const char* b3 = b2 + kstep;
;             if (last && has_next) S.a_ready(nxt);
;             if constexpr (SP2) {
;             PG8_LDB(B0, 0, 0); PG8_LDB(B1, 0, 1); PG8_SCHED; PG8_LDA(At, 0, 0); PG8_STAGE(PG8_SA(1, 1), a1 + hstep, voffA);
;             PG8_WAIT_V(8); PG8_WAIT_L(0); PG8_BAR; PG8_MMA(0, 0, At, B0); PG8_MMA(0, 1, At, B1); PG8_BAR; PG8_SCHED;
;             PG8_LDA(At, 0, 1); PG8_STAGE(PG8_SB(0, 0), b2, voffB); PG8_STAGE(PG8_SB(0, 1), b2 + hstep, voffB); PG8_STAGE(PG8_SA(0, 0), a2, voffA);
;             PG8_WAIT_V(8); PG8_WAIT_L(0); PG8_BAR; PG8_MMA(1, 0, At, B0); PG8_MMA(1, 1, At, B1); PG8_BAR; PG8_SCHED;
.LBB0_220:
	s_add_u32 s18, s60, 0xfffc0080
	s_addc_u32 s38, s61, -1
	s_add_i32 s39, 0, 0x10000
	s_cmp_eq_u32 s82, 12
	s_cselect_b32 s65, s47, s38
	s_cselect_b32 s64, s78, s18
	v_add_u32_e32 v145, s39, v141
	s_cselect_b32 s57, s49, s81
	s_cselect_b32 s56, s79, s80
	s_add_i32 s18, 0, 0x14000
	ds_read_b128 v[146:149], v145
	ds_read_b128 v[150:153], v145 offset:1024
	ds_read_b128 v[154:157], v145 offset:2048
	ds_read_b128 v[158:161], v145 offset:3072
	v_add_u32_e32 v145, s18, v141
	ds_read_b128 v[162:165], v145
	ds_read_b128 v[166:169], v145 offset:1024
	ds_read_b128 v[170:173], v145 offset:2048
	ds_read_b128 v[174:177], v145 offset:3072
	v_lshl_add_u64 v[194:195], s[60:61], 0, v[136:137]
	s_add_i32 m0, s29, 0xc000
	ds_read_b128 v[178:181], v144
	ds_read_b128 v[182:185], v144 offset:1024
	ds_read_b128 v[186:189], v144 offset:2048
	ds_read_b128 v[190:193], v144 offset:3072
	ds_read_b128 v[202:205], v144 offset:4096
	ds_read_b128 v[206:209], v144 offset:5120
	ds_read_b128 v[210:213], v144 offset:6144
	ds_read_b128 v[214:217], v144 offset:7168
	global_load_lds_dwordx4 v[194:195], off
	v_lshl_add_u64 v[194:195], s[60:61], 0, v[138:139]
	s_add_i32 m0, s29, 0xe000
	s_nop 0
	global_load_lds_dwordx4 v[194:195], off
	s_waitcnt vmcnt(8)
	s_waitcnt lgkmcnt(0)
	s_barrier
	s_setprio 1
	v_mfma_f32_16x16x32_bf16 v[114:117], v[146:149], v[178:181], v[114:117]
	v_mfma_f32_16x16x32_bf16 v[114:117], v[150:153], v[182:185], v[114:117]
	v_mfma_f32_16x16x32_bf16 v[98:101], v[146:149], v[186:189], v[98:101]
	v_mfma_f32_16x16x32_bf16 v[98:101], v[150:153], v[190:193], v[98:101]
	v_mfma_f32_16x16x32_bf16 v[82:85], v[146:149], v[202:205], v[82:85]
	v_mfma_f32_16x16x32_bf16 v[82:85], v[150:153], v[206:209], v[82:85]
	v_mfma_f32_16x16x32_bf16 v[66:69], v[146:149], v[210:213], v[66:69]
	v_mfma_f32_16x16x32_bf16 v[66:69], v[150:153], v[214:217], v[66:69]
	v_mfma_f32_16x16x32_bf16 v[118:121], v[154:157], v[178:181], v[118:121]
	v_mfma_f32_16x16x32_bf16 v[118:121], v[158:161], v[182:185], v[118:121]
	v_mfma_f32_16x16x32_bf16 v[102:105], v[154:157], v[186:189], v[102:105]
	v_mfma_f32_16x16x32_bf16 v[102:105], v[158:161], v[190:193], v[102:105]
	v_mfma_f32_16x16x32_bf16 v[86:89], v[154:157], v[202:205], v[86:89]
	v_mfma_f32_16x16x32_bf16 v[86:89], v[158:161], v[206:209], v[86:89]
	v_mfma_f32_16x16x32_bf16 v[70:73], v[154:157], v[210:213], v[70:73]
	v_mfma_f32_16x16x32_bf16 v[70:73], v[158:161], v[214:217], v[70:73]
	v_mfma_f32_16x16x32_bf16 v[122:125], v[162:165], v[178:181], v[122:125]
	v_mfma_f32_16x16x32_bf16 v[122:125], v[166:169], v[182:185], v[122:125]
	v_mfma_f32_16x16x32_bf16 v[106:109], v[162:165], v[186:189], v[106:109]
	v_mfma_f32_16x16x32_bf16 v[106:109], v[166:169], v[190:193], v[106:109]
	v_mfma_f32_16x16x32_bf16 v[90:93], v[162:165], v[202:205], v[90:93]
	v_mfma_f32_16x16x32_bf16 v[90:93], v[166:169], v[206:209], v[90:93]
	v_mfma_f32_16x16x32_bf16 v[74:77], v[162:165], v[210:213], v[74:77]
	v_mfma_f32_16x16x32_bf16 v[74:77], v[166:169], v[214:217], v[74:77]
	v_mfma_f32_16x16x32_bf16 v[126:129], v[170:173], v[178:181], v[126:129]
	v_mfma_f32_16x16x32_bf16 v[126:129], v[174:177], v[182:185], v[126:129]
	v_mfma_f32_16x16x32_bf16 v[110:113], v[170:173], v[186:189], v[110:113]
	v_mfma_f32_16x16x32_bf16 v[110:113], v[174:177], v[190:193], v[110:113]
	v_mfma_f32_16x16x32_bf16 v[94:97], v[170:173], v[202:205], v[94:97]
	v_mfma_f32_16x16x32_bf16 v[94:97], v[174:177], v[206:209], v[94:97]
	v_mfma_f32_16x16x32_bf16 v[78:81], v[170:173], v[210:213], v[78:81]
	v_mfma_f32_16x16x32_bf16 v[78:81], v[174:177], v[214:217], v[78:81]
	s_setprio 0
	s_barrier
	s_add_i32 s38, s39, s27
	v_lshl_add_u64 v[194:195], s[56:57], 0, v[0:1]
	s_mov_b32 m0, s38
	ds_read_b128 v[178:181], v144 offset:16384
	ds_read_b128 v[182:185], v144 offset:17408
	ds_read_b128 v[186:189], v144 offset:18432
	ds_read_b128 v[190:193], v144 offset:19456
	ds_read_b128 v[202:205], v144 offset:20480
	ds_read_b128 v[206:209], v144 offset:21504
	ds_read_b128 v[210:213], v144 offset:22528
	ds_read_b128 v[214:217], v144 offset:23552
	global_load_lds_dwordx4 v[194:195], off
	s_add_i32 m0, s38, 0x2000
	s_add_u32 s38, s56, 0x40000
	v_lshl_add_u64 v[218:219], s[56:57], 0, v[130:131]
	s_addc_u32 s39, s57, 0
	s_add_i32 s18, s18, s27
	global_load_lds_dwordx4 v[218:219], off
	v_lshl_add_u64 v[220:221], s[38:39], 0, v[0:1]
	s_mov_b32 m0, s18
	v_lshl_add_u64 v[222:223], s[64:65], 0, v[132:133]
	global_load_lds_dwordx4 v[220:221], off
	v_lshl_add_u64 v[220:221], s[38:39], 0, v[130:131]
	s_add_i32 m0, s18, 0x2000
	s_nop 0
	global_load_lds_dwordx4 v[220:221], off
	v_lshl_add_u64 v[220:221], s[64:65], 0, v[134:135]
	s_mov_b32 m0, s29
	s_nop 0
	global_load_lds_dwordx4 v[220:221], off
	s_mov_b32 m0, s33
	s_nop 0
	global_load_lds_dwordx4 v[222:223], off
	s_waitcnt vmcnt(8)
	s_waitcnt lgkmcnt(0)
	s_barrier
; #define PG8_STAGE(bufoff, gbase, voff) do { _Pragma("unroll") for (int _i = 0; _i < 2; ++_i) \
;         __builtin_amdgcn_global_load_lds((const unsigned*)((const char*)(gbase) + (voff)[_i]), (PG8_LAS unsigned*)(lds + (bufoff) + ldsw + _i * 8192), 16, 0, 0); } while (0)
; #define PG8_LDA(dst, b, h) do { _Pragma("unroll") for (int m = 0; m < 4; ++m) _Pragma("unroll") for (int k = 0; k < 2; ++k) dst[m][k] = *(const PG8_LAS bf16x8*)(lds + PG8_SA(b, h) + aoff + m * 2048 + k * 1024); } while (0)
; #define PG8_LDB(dst, b, h) do { _Pragma("unroll") for (int n = 0; n < 2; ++n) _Pragma("unroll") for (int k = 0; k < 2; ++k) dst[n][k] = *(const PG8_LAS bf16x8*)(lds + PG8_SB(b, h) + boff + n * 2048 + k * 1024); } while (0)
; #define PG8_MMA(ai, bj, At, Bt) do { __builtin_amdgcn_s_setprio(1); _Pragma("unroll") for (int m = 0; m < 4; ++m) _Pragma("unroll") for (int n = 0; n < 2; ++n) _Pragma("unroll") for (int k = 0; k < 2; ++k) \
;         acc[ai][bj][m][n] = __builtin_amdgcn_mfma_f32_16x16x32_bf16(Bt[n][k], At[m][k], acc[ai][bj][m][n], 0, 0, 0); __builtin_amdgcn_s_setprio(0); } while (0)
; #define PG8_WAIT_V(n) asm volatile("s_waitcnt vmcnt(" #n ")" ::: "memory")
; #define PG8_WAIT_L(n) asm volatile("s_waitcnt lgkmcnt(" #n ")" ::: "memory")
; #define PG8_BAR __builtin_amdgcn_s_barrier()
; #define PG8_SCHED __builtin_amdgcn_sched_barrier(0)
; template <class Epi, class Sched, bool ALIGN_EPI = false, bool SP2 = false>
; __device__ __forceinline__ void gemm_phase(PG8_LAS unsigned char* lds, const Gemm g, const Sched& S, const Epi& E) {
;     ...
;             PG8_WAIT_V(8); PG8_WAIT_L(0); PG8_BAR; PG8_MMA(1, 0, At, B0); PG8_MMA(1, 1, At, B1); PG8_BAR; PG8_SCHED;
;             PG8_LDB(B0, 1, 0); PG8_LDB(B1, 1, 1); PG8_SCHED; PG8_LDA(At, 1, 0); PG8_STAGE(PG8_SA(0, 1), a2 + hstep, voffA);
;             PG8_WAIT_V(8); PG8_WAIT_L(0); PG8_BAR; PG8_MMA(0, 0, At, B0); PG8_MMA(0, 1, At, B1); PG8_BAR; PG8_SCHED;
	s_setprio 1
	v_mfma_f32_16x16x32_bf16 v[50:53], v[146:149], v[178:181], v[50:53]
	v_mfma_f32_16x16x32_bf16 v[50:53], v[150:153], v[182:185], v[50:53]
	v_mfma_f32_16x16x32_bf16 v[34:37], v[146:149], v[186:189], v[34:37]
	v_mfma_f32_16x16x32_bf16 v[34:37], v[150:153], v[190:193], v[34:37]
	v_mfma_f32_16x16x32_bf16 v[18:21], v[146:149], v[202:205], v[18:21]
	v_mfma_f32_16x16x32_bf16 v[18:21], v[150:153], v[206:209], v[18:21]
	v_mfma_f32_16x16x32_bf16 v[2:5], v[146:149], v[210:213], v[2:5]
	v_mfma_f32_16x16x32_bf16 v[2:5], v[150:153], v[214:217], v[2:5]
	v_mfma_f32_16x16x32_bf16 v[54:57], v[154:157], v[178:181], v[54:57]
	v_mfma_f32_16x16x32_bf16 v[54:57], v[158:161], v[182:185], v[54:57]
	v_mfma_f32_16x16x32_bf16 v[38:41], v[154:157], v[186:189], v[38:41]
	v_mfma_f32_16x16x32_bf16 v[38:41], v[158:161], v[190:193], v[38:41]
	v_mfma_f32_16x16x32_bf16 v[22:25], v[154:157], v[202:205], v[22:25]
	v_mfma_f32_16x16x32_bf16 v[22:25], v[158:161], v[206:209], v[22:25]
	v_mfma_f32_16x16x32_bf16 v[6:9], v[154:157], v[210:213], v[6:9]
	v_mfma_f32_16x16x32_bf16 v[6:9], v[158:161], v[214:217], v[6:9]
	v_mfma_f32_16x16x32_bf16 v[58:61], v[162:165], v[178:181], v[58:61]
	v_mfma_f32_16x16x32_bf16 v[58:61], v[166:169], v[182:185], v[58:61]
	v_mfma_f32_16x16x32_bf16 v[42:45], v[162:165], v[186:189], v[42:45]
	v_mfma_f32_16x16x32_bf16 v[42:45], v[166:169], v[190:193], v[42:45]
	v_mfma_f32_16x16x32_bf16 v[26:29], v[162:165], v[202:205], v[26:29]
	v_mfma_f32_16x16x32_bf16 v[26:29], v[166:169], v[206:209], v[26:29]
	v_mfma_f32_16x16x32_bf16 v[10:13], v[162:165], v[210:213], v[10:13]
	v_mfma_f32_16x16x32_bf16 v[10:13], v[166:169], v[214:217], v[10:13]
	v_mfma_f32_16x16x32_bf16 v[62:65], v[170:173], v[178:181], v[62:65]
	v_mfma_f32_16x16x32_bf16 v[62:65], v[174:177], v[182:185], v[62:65]
	v_mfma_f32_16x16x32_bf16 v[46:49], v[170:173], v[186:189], v[46:49]
	v_mfma_f32_16x16x32_bf16 v[46:49], v[174:177], v[190:193], v[46:49]
	v_mfma_f32_16x16x32_bf16 v[30:33], v[170:173], v[202:205], v[30:33]
	v_mfma_f32_16x16x32_bf16 v[30:33], v[174:177], v[206:209], v[30:33]
	v_mfma_f32_16x16x32_bf16 v[14:17], v[170:173], v[210:213], v[14:17]
	v_mfma_f32_16x16x32_bf16 v[14:17], v[174:177], v[214:217], v[14:17]
	s_setprio 0
	s_barrier
	s_add_i32 s18, 0, 0x18000
	v_add_u32_e32 v145, s18, v141
	s_add_i32 s83, 0, 0x1c000
	ds_read_b128 v[146:149], v145
	ds_read_b128 v[150:153], v145 offset:1024
	ds_read_b128 v[154:157], v145 offset:2048
	ds_read_b128 v[158:161], v145 offset:3072
	v_add_u32_e32 v145, s83, v141
	ds_read_b128 v[162:165], v145
	ds_read_b128 v[166:169], v145 offset:1024
	ds_read_b128 v[170:173], v145 offset:2048
	ds_read_b128 v[174:177], v145 offset:3072
	s_add_u32 s38, s64, 0x40000
	s_addc_u32 s39, s65, 0
	s_mov_b32 m0, s58
	v_lshl_add_u64 v[224:225], s[38:39], 0, v[134:135]
	ds_read_b128 v[178:181], v144 offset:32768
	ds_read_b128 v[182:185], v144 offset:33792
	ds_read_b128 v[186:189], v144 offset:34816
	ds_read_b128 v[190:193], v144 offset:35840
	ds_read_b128 v[202:205], v144 offset:36864
	ds_read_b128 v[206:209], v144 offset:37888
	ds_read_b128 v[210:213], v144 offset:38912
	ds_read_b128 v[214:217], v144 offset:39936
	global_load_lds_dwordx4 v[224:225], off
	v_lshl_add_u64 v[224:225], s[38:39], 0, v[132:133]
	s_mov_b32 m0, s69
	s_nop 0
	global_load_lds_dwordx4 v[224:225], off
	s_waitcnt vmcnt(8)
	s_waitcnt lgkmcnt(0)
	s_barrier
	s_setprio 1
	v_mfma_f32_16x16x32_bf16 v[114:117], v[146:149], v[178:181], v[114:117]
	v_mfma_f32_16x16x32_bf16 v[114:117], v[150:153], v[182:185], v[114:117]
	v_mfma_f32_16x16x32_bf16 v[98:101], v[146:149], v[186:189], v[98:101]
	v_mfma_f32_16x16x32_bf16 v[98:101], v[150:153], v[190:193], v[98:101]
	v_mfma_f32_16x16x32_bf16 v[82:85], v[146:149], v[202:205], v[82:85]
	v_mfma_f32_16x16x32_bf16 v[82:85], v[150:153], v[206:209], v[82:85]
	v_mfma_f32_16x16x32_bf16 v[66:69], v[146:149], v[210:213], v[66:69]
	v_mfma_f32_16x16x32_bf16 v[66:69], v[150:153], v[214:217], v[66:69]
	v_mfma_f32_16x16x32_bf16 v[118:121], v[154:157], v[178:181], v[118:121]
	v_mfma_f32_16x16x32_bf16 v[118:121], v[158:161], v[182:185], v[118:121]
	v_mfma_f32_16x16x32_bf16 v[102:105], v[154:157], v[186:189], v[102:105]
	v_mfma_f32_16x16x32_bf16 v[102:105], v[158:161], v[190:193], v[102:105]
	v_mfma_f32_16x16x32_bf16 v[86:89], v[154:157], v[202:205], v[86:89]
	v_mfma_f32_16x16x32_bf16 v[86:89], v[158:161], v[206:209], v[86:89]
	v_mfma_f32_16x16x32_bf16 v[70:73], v[154:157], v[210:213], v[70:73]
	v_mfma_f32_16x16x32_bf16 v[70:73], v[158:161], v[214:217], v[70:73]
	v_mfma_f32_16x16x32_bf16 v[122:125], v[162:165], v[178:181], v[122:125]
	v_mfma_f32_16x16x32_bf16 v[122:125], v[166:169], v[182:185], v[122:125]
	v_mfma_f32_16x16x32_bf16 v[106:109], v[162:165], v[186:189], v[106:109]
	v_mfma_f32_16x16x32_bf16 v[106:109], v[166:169], v[190:193], v[106:109]
	v_mfma_f32_16x16x32_bf16 v[90:93], v[162:165], v[202:205], v[90:93]
	v_mfma_f32_16x16x32_bf16 v[90:93], v[166:169], v[206:209], v[90:93]
	v_mfma_f32_16x16x32_bf16 v[74:77], v[162:165], v[210:213], v[74:77]
	v_mfma_f32_16x16x32_bf16 v[74:77], v[166:169], v[214:217], v[74:77]
	v_mfma_f32_16x16x32_bf16 v[126:129], v[170:173], v[178:181], v[126:129]
	v_mfma_f32_16x16x32_bf16 v[126:129], v[174:177], v[182:185], v[126:129]
	v_mfma_f32_16x16x32_bf16 v[110:113], v[170:173], v[186:189], v[110:113]
	v_mfma_f32_16x16x32_bf16 v[110:113], v[174:177], v[190:193], v[110:113]
	v_mfma_f32_16x16x32_bf16 v[94:97], v[170:173], v[202:205], v[94:97]
	v_mfma_f32_16x16x32_bf16 v[94:97], v[174:177], v[206:209], v[94:97]
	v_mfma_f32_16x16x32_bf16 v[78:81], v[170:173], v[210:213], v[78:81]
	v_mfma_f32_16x16x32_bf16 v[78:81], v[174:177], v[214:217], v[78:81]
	s_setprio 0
	s_barrier
; #define PG8_STAGE(bufoff, gbase, voff) do { _Pragma("unroll") for (int _i = 0; _i < 2; ++_i) \
;         __builtin_amdgcn_global_load_lds((const unsigned*)((const char*)(gbase) + (voff)[_i]), (PG8_LAS unsigned*)(lds + (bufoff) + ldsw + _i * 8192), 16, 0, 0); } while (0)
; #define PG8_LDA(dst, b, h) do { _Pragma("unroll") for (int m = 0; m < 4; ++m) _Pragma("unroll") for (int k = 0; k < 2; ++k) dst[m][k] = *(const PG8_LAS bf16x8*)(lds + PG8_SA(b, h) + aoff + m * 2048 + k * 1024); } while (0)
; #define PG8_WAIT_V(n) asm volatile("s_waitcnt vmcnt(" #n ")" ::: "memory")
; template <class Epi, class Sched, bool ALIGN_EPI = false, bool SP2 = false>
; __device__ __forceinline__ void gemm_phase(PG8_LAS unsigned char* lds, const Gemm g, const Sched& S, const Epi& E) {
;     ...
;             PG8_LDA(At, 1, 1); PG8_STAGE(PG8_SB(1, 0), b3, voffB); PG8_STAGE(PG8_SB(1, 1), b3 + hstep, voffB); PG8_STAGE(PG8_SA(1, 0), a3, voffA);
;             PG8_WAIT_V(8); PG8_WAIT_L(0); PG8_BAR; PG8_MMA(1, 0, At, B0); PG8_MMA(1, 1, At, B1); PG8_BAR; PG8_SCHED;
;             } else {
;             PG8_LDB(B0, 0, 0); PG8_SCHED; PG8_LDA(At, 0, 0); PG8_STAGE(PG8_SA(1, 1), a1 + hstep, voffA);
;             PG8_WAIT_L(8); PG8_BAR; PG8_WAIT_L(0); PG8_MMA(0, 0, At, B0); PG8_BAR; PG8_SCHED;
;             PG8_LDB(B1, 0, 1); PG8_STAGE(PG8_SB(0, 0), b2, voffB);
;             PG8_BAR; PG8_WAIT_L(0); PG8_MMA(0, 1, At, B1); PG8_BAR;
;             PG8_LDA(At, 0, 1); PG8_STAGE(PG8_SA(0, 0), a2, voffA);
;             PG8_BAR; PG8_WAIT_L(0); PG8_MMA(1, 0, At, B0); PG8_BAR; PG8_SCHED;
;             PG8_STAGE(PG8_SB(0, 1), b2 + hstep, voffB);
;             PG8_WAIT_V(6); PG8_BAR; PG8_MMA(1, 1, At, B1); PG8_BAR;
;             PG8_LDB(B0, 1, 0); PG8_SCHED; PG8_LDA(At, 1, 0); PG8_STAGE(PG8_SA(0, 1), a2 + hstep, voffA);
;             PG8_WAIT_L(8); PG8_BAR; PG8_WAIT_L(0); PG8_MMA(0, 0, At, B0); PG8_BAR; PG8_SCHED;
;             PG8_LDB(B1, 1, 1); PG8_STAGE(PG8_SB(1, 0), b3, voffB);
;             PG8_BAR; PG8_WAIT_L(0); PG8_MMA(0, 1, At, B1); PG8_BAR;
;             PG8_LDA(At, 1, 1); PG8_STAGE(PG8_SA(1, 0), a3, voffA);
;             PG8_BAR; PG8_WAIT_L(0); PG8_MMA(1, 0, At, B0); PG8_BAR; PG8_SCHED;
;             PG8_STAGE(PG8_SB(1, 1), b3 + hstep, voffB);
;             PG8_WAIT_V(6); PG8_BAR; PG8_MMA(1, 1, At, B1); PG8_BAR;
;             }
;         }
;         if constexpr (ALIGN_EPI) { if (wr == 0) PG8_BAR; }
	s_add_i32 s18, s18, s27
	v_lshl_add_u64 v[194:195], v[194:195], 0, s[30:31]
	s_mov_b32 m0, s18
	ds_read_b128 v[178:181], v144 offset:49152
	ds_read_b128 v[182:185], v144 offset:50176
	ds_read_b128 v[186:189], v144 offset:51200
	ds_read_b128 v[190:193], v144 offset:52224
	ds_read_b128 v[202:205], v144 offset:53248
	ds_read_b128 v[206:209], v144 offset:54272
	ds_read_b128 v[210:213], v144 offset:55296
	ds_read_b128 v[214:217], v144 offset:56320
	global_load_lds_dwordx4 v[194:195], off
	s_add_i32 m0, s18, 0x2000
	s_add_u32 s38, s56, 0x40080
	v_lshl_add_u64 v[194:195], v[218:219], 0, s[30:31]
	s_addc_u32 s39, s57, 0
	s_add_i32 s18, s83, s27
	global_load_lds_dwordx4 v[194:195], off
	v_lshl_add_u64 v[194:195], s[38:39], 0, v[0:1]
	s_mov_b32 m0, s18
	s_nop 0
	global_load_lds_dwordx4 v[194:195], off
	v_lshl_add_u64 v[194:195], s[38:39], 0, v[130:131]
	s_add_i32 m0, s18, 0x2000
	s_nop 0
	global_load_lds_dwordx4 v[194:195], off
	v_lshl_add_u64 v[194:195], v[220:221], 0, s[30:31]
	s_mov_b32 m0, s71
	s_nop 0
	global_load_lds_dwordx4 v[194:195], off
	v_lshl_add_u64 v[194:195], v[222:223], 0, s[30:31]
	s_mov_b32 m0, s72
	s_nop 0
	global_load_lds_dwordx4 v[194:195], off
	s_waitcnt vmcnt(8)
	s_waitcnt lgkmcnt(0)
	s_barrier
	s_setprio 1
	v_mfma_f32_16x16x32_bf16 v[50:53], v[146:149], v[178:181], v[50:53]
	v_mfma_f32_16x16x32_bf16 v[50:53], v[150:153], v[182:185], v[50:53]
	v_mfma_f32_16x16x32_bf16 v[34:37], v[146:149], v[186:189], v[34:37]
	v_mfma_f32_16x16x32_bf16 v[34:37], v[150:153], v[190:193], v[34:37]
	v_mfma_f32_16x16x32_bf16 v[18:21], v[146:149], v[202:205], v[18:21]
	v_mfma_f32_16x16x32_bf16 v[18:21], v[150:153], v[206:209], v[18:21]
	v_mfma_f32_16x16x32_bf16 v[2:5], v[146:149], v[210:213], v[2:5]
	v_mfma_f32_16x16x32_bf16 v[2:5], v[150:153], v[214:217], v[2:5]
	v_mfma_f32_16x16x32_bf16 v[54:57], v[154:157], v[178:181], v[54:57]
	v_mfma_f32_16x16x32_bf16 v[54:57], v[158:161], v[182:185], v[54:57]
	v_mfma_f32_16x16x32_bf16 v[38:41], v[154:157], v[186:189], v[38:41]
	v_mfma_f32_16x16x32_bf16 v[38:41], v[158:161], v[190:193], v[38:41]
	v_mfma_f32_16x16x32_bf16 v[22:25], v[154:157], v[202:205], v[22:25]
	v_mfma_f32_16x16x32_bf16 v[22:25], v[158:161], v[206:209], v[22:25]
	v_mfma_f32_16x16x32_bf16 v[6:9], v[154:157], v[210:213], v[6:9]
	v_mfma_f32_16x16x32_bf16 v[6:9], v[158:161], v[214:217], v[6:9]
	v_mfma_f32_16x16x32_bf16 v[58:61], v[162:165], v[178:181], v[58:61]
	v_mfma_f32_16x16x32_bf16 v[58:61], v[166:169], v[182:185], v[58:61]
	v_mfma_f32_16x16x32_bf16 v[42:45], v[162:165], v[186:189], v[42:45]
	v_mfma_f32_16x16x32_bf16 v[42:45], v[166:169], v[190:193], v[42:45]
	v_mfma_f32_16x16x32_bf16 v[26:29], v[162:165], v[202:205], v[26:29]
	v_mfma_f32_16x16x32_bf16 v[26:29], v[166:169], v[206:209], v[26:29]
	v_mfma_f32_16x16x32_bf16 v[10:13], v[162:165], v[210:213], v[10:13]
	v_mfma_f32_16x16x32_bf16 v[10:13], v[166:169], v[214:217], v[10:13]
	v_mfma_f32_16x16x32_bf16 v[62:65], v[170:173], v[178:181], v[62:65]
	v_mfma_f32_16x16x32_bf16 v[62:65], v[174:177], v[182:185], v[62:65]
	v_mfma_f32_16x16x32_bf16 v[46:49], v[170:173], v[186:189], v[46:49]
	v_mfma_f32_16x16x32_bf16 v[46:49], v[174:177], v[190:193], v[46:49]
	v_mfma_f32_16x16x32_bf16 v[30:33], v[170:173], v[202:205], v[30:33]
	v_mfma_f32_16x16x32_bf16 v[30:33], v[174:177], v[206:209], v[30:33]
	v_mfma_f32_16x16x32_bf16 v[14:17], v[170:173], v[210:213], v[14:17]
	v_mfma_f32_16x16x32_bf16 v[14:17], v[174:177], v[214:217], v[14:17]
	s_setprio 0
	s_barrier
	s_add_i32 s82, s82, 2
	s_add_u32 s60, s60, 0x100
	s_addc_u32 s61, s61, 0
	s_add_u32 s80, s80, 0x100
	s_addc_u32 s81, s81, 0
	s_cmp_gt_u32 s82, 13
	s_cbranch_scc0 .LBB0_220
	s_and_b64 vcc, exec, s[44:45]
	s_cbranch_vccz .LBB0_223
	s_barrier

; #define PG8_STAGE(bufoff, gbase, voff) do { _Pragma("unroll") for (int _i = 0; _i < 2; ++_i) \
;         __builtin_amdgcn_global_load_lds((const unsigned*)((const char*)(gbase) + (voff)[_i]), (PG8_LAS unsigned*)(lds + (bufoff) + ldsw + _i * 8192), 16, 0, 0); } while (0)
; #define PG8_LDA(dst, b, h) do { _Pragma("unroll") for (int m = 0; m < 4; ++m) _Pragma("unroll") for (int k = 0; k < 2; ++k) dst[m][k] = *(const PG8_LAS bf16x8*)(lds + PG8_SA(b, h) + aoff + m * 2048 + k * 1024); } while (0)
; #define PG8_LDB(dst, b, h) do { _Pragma("unroll") for (int n = 0; n < 2; ++n) _Pragma("unroll") for (int k = 0; k < 2; ++k) dst[n][k] = *(const PG8_LAS bf16x8*)(lds + PG8_SB(b, h) + boff + n * 2048 + k * 1024); } while (0)
; #define PG8_WAIT_V(n) asm volatile("s_waitcnt vmcnt(" #n ")" ::: "memory")
; #define PG8_WAIT_L(n) asm volatile("s_waitcnt lgkmcnt(" #n ")" ::: "memory")
; #define PG8_BAR __builtin_amdgcn_s_barrier()
; #define PG8_SCHED __builtin_amdgcn_sched_barrier(0)
; template <class Epi, class Sched, bool ALIGN_EPI = false, bool SP2 = false>
; __device__ __forceinline__ void gemm_phase(PG8_LAS unsigned char* lds, const Gemm g, const Sched& S, const Epi& E) {
;     ...
;         const bool has_next = S.next(ui + 1, nxt);
;         const char* nA = has_next ? (const char*)g.A + (size_t)nxt.pm * tstep : cA; const char* nB = has_next ? (const char*)g.Bt + (size_t)nxt.pn * tstep : cB;
;         for (int t = 0; t < nt; t += 2) {
;             const bool last = (t == nt - 2);
;             const char* a1 = cA + (size_t)(t + 1) * kstep;
;             const char* a2 = last ? nA : cA + (size_t)(t + 2) * kstep; const char* b2 = last ? nB : cB + (size_t)(t + 2) * kstep;
;             const char* a3 = a2 + kstep; const char* b3 = b2 + kstep;
;             if (last && has_next) S.a_ready(nxt);
;             if constexpr (SP2) {
;             PG8_LDB(B0, 0, 0); PG8_LDB(B1, 0, 1); PG8_SCHED; PG8_LDA(At, 0, 0); PG8_STAGE(PG8_SA(1, 1), a1 + hstep, voffA);
;             PG8_WAIT_V(8); PG8_WAIT_L(0); PG8_BAR; PG8_MMA(0, 0, At, B0); PG8_MMA(0, 1, At, B1); PG8_BAR; PG8_SCHED;
;             PG8_LDA(At, 0, 1); PG8_STAGE(PG8_SB(0, 0), b2, voffB); PG8_STAGE(PG8_SB(0, 1), b2 + hstep, voffB); PG8_STAGE(PG8_SA(0, 0), a2, voffA);
;             PG8_WAIT_V(8); PG8_WAIT_L(0); PG8_BAR; PG8_MMA(1, 0, At, B0); PG8_MMA(1, 1, At, B1); PG8_BAR; PG8_SCHED;
.LBB0_274:
	s_add_i32 vcc_lo, s46, 2
	s_add_u32 s38, s48, 0x80
	s_addc_u32 s39, s49, 0
	s_add_i32 vcc_hi, 0, 0x10000
	s_cmp_eq_u32 s99, s46
	s_cselect_b32 s47, s81, s39
	s_cselect_b32 s46, s80, s38
	s_cselect_b32 s39, s83, s51
	s_cselect_b32 s38, s82, s50
	s_add_i32 s18, 0, 0x14000
	v_add_u32_e32 v142, vcc_hi, v245
	v_add_u32_e32 v158, s18, v245
	ds_read_b128 v[110:113], v142
	ds_read_b128 v[118:121], v142 offset:1024
	ds_read_b128 v[138:141], v142 offset:2048
	ds_read_b128 v[142:145], v142 offset:3072
	ds_read_b128 v[146:149], v158
	ds_read_b128 v[150:153], v158 offset:1024
	ds_read_b128 v[154:157], v158 offset:2048
	ds_read_b128 v[158:161], v158 offset:3072
	v_lshl_add_u64 v[210:211], s[48:49], 0, v[206:207]
	s_add_i32 m0, s92, 0xc000
	ds_read_b128 v[162:165], v247
	ds_read_b128 v[166:169], v247 offset:1024
	ds_read_b128 v[170:173], v247 offset:2048
	ds_read_b128 v[174:177], v247 offset:3072
	ds_read_b128 v[178:181], v247 offset:4096
	ds_read_b128 v[182:185], v247 offset:5120
	ds_read_b128 v[186:189], v247 offset:6144
	ds_read_b128 v[190:193], v247 offset:7168
	global_load_lds_dwordx4 v[210:211], off
	v_lshl_add_u64 v[210:211], s[48:49], 0, v[208:209]
	s_add_i32 m0, s92, 0xe000
	s_nop 0
	global_load_lds_dwordx4 v[210:211], off
	s_waitcnt vmcnt(8)
	s_waitcnt lgkmcnt(0)
	s_barrier
	s_setprio 1
	v_mfma_f32_16x16x32_bf16 v[130:133], v[110:113], v[162:165], v[130:133]
	v_mfma_f32_16x16x32_bf16 v[130:133], v[118:121], v[166:169], v[130:133]
	v_mfma_f32_16x16x32_bf16 v[114:117], v[110:113], v[170:173], v[114:117]
	v_mfma_f32_16x16x32_bf16 v[114:117], v[118:121], v[174:177], v[114:117]
	v_mfma_f32_16x16x32_bf16 v[94:97], v[110:113], v[178:181], v[94:97]
	v_mfma_f32_16x16x32_bf16 v[94:97], v[118:121], v[182:185], v[94:97]
	v_mfma_f32_16x16x32_bf16 v[78:81], v[110:113], v[186:189], v[78:81]
	v_mfma_f32_16x16x32_bf16 v[78:81], v[118:121], v[190:193], v[78:81]
	v_mfma_f32_16x16x32_bf16 v[134:137], v[138:141], v[162:165], v[134:137]
	v_mfma_f32_16x16x32_bf16 v[134:137], v[142:145], v[166:169], v[134:137]
	v_mfma_f32_16x16x32_bf16 v[106:109], v[138:141], v[170:173], v[106:109]
	v_mfma_f32_16x16x32_bf16 v[106:109], v[142:145], v[174:177], v[106:109]
	v_mfma_f32_16x16x32_bf16 v[90:93], v[138:141], v[178:181], v[90:93]
	v_mfma_f32_16x16x32_bf16 v[90:93], v[142:145], v[182:185], v[90:93]
	v_mfma_f32_16x16x32_bf16 v[74:77], v[138:141], v[186:189], v[74:77]
	v_mfma_f32_16x16x32_bf16 v[74:77], v[142:145], v[190:193], v[74:77]
	v_mfma_f32_16x16x32_bf16 v[126:129], v[146:149], v[162:165], v[126:129]
	v_mfma_f32_16x16x32_bf16 v[126:129], v[150:153], v[166:169], v[126:129]
	v_mfma_f32_16x16x32_bf16 v[102:105], v[146:149], v[170:173], v[102:105]
	v_mfma_f32_16x16x32_bf16 v[102:105], v[150:153], v[174:177], v[102:105]
	v_mfma_f32_16x16x32_bf16 v[86:89], v[146:149], v[178:181], v[86:89]
	v_mfma_f32_16x16x32_bf16 v[86:89], v[150:153], v[182:185], v[86:89]
	v_mfma_f32_16x16x32_bf16 v[70:73], v[146:149], v[186:189], v[70:73]
	v_mfma_f32_16x16x32_bf16 v[70:73], v[150:153], v[190:193], v[70:73]
	v_mfma_f32_16x16x32_bf16 v[122:125], v[154:157], v[162:165], v[122:125]
	v_mfma_f32_16x16x32_bf16 v[122:125], v[158:161], v[166:169], v[122:125]
	v_mfma_f32_16x16x32_bf16 v[98:101], v[154:157], v[170:173], v[98:101]
	v_mfma_f32_16x16x32_bf16 v[98:101], v[158:161], v[174:177], v[98:101]
	v_mfma_f32_16x16x32_bf16 v[82:85], v[154:157], v[178:181], v[82:85]
	v_mfma_f32_16x16x32_bf16 v[82:85], v[158:161], v[182:185], v[82:85]
	v_mfma_f32_16x16x32_bf16 v[66:69], v[154:157], v[186:189], v[66:69]
	v_mfma_f32_16x16x32_bf16 v[66:69], v[158:161], v[190:193], v[66:69]
	s_setprio 0
	s_barrier
	s_add_i32 vcc_hi, vcc_hi, s6
	v_lshl_add_u64 v[210:211], s[38:39], 0, v[0:1]
	s_mov_b32 m0, vcc_hi
	ds_read_b128 v[162:165], v247 offset:16384
	ds_read_b128 v[166:169], v247 offset:17408
	ds_read_b128 v[170:173], v247 offset:18432
	ds_read_b128 v[174:177], v247 offset:19456
	ds_read_b128 v[178:181], v247 offset:20480
	ds_read_b128 v[182:185], v247 offset:21504
	ds_read_b128 v[186:189], v247 offset:22528
	ds_read_b128 v[190:193], v247 offset:23552
	global_load_lds_dwordx4 v[210:211], off
	s_add_i32 m0, vcc_hi, 0x2000
	v_lshl_add_u64 v[212:213], s[38:39], 0, v[204:205]
	s_add_u32 s38, s38, s58
	s_addc_u32 s39, s39, 0
	s_add_i32 s18, s18, s6
	global_load_lds_dwordx4 v[212:213], off
	v_lshl_add_u64 v[214:215], s[38:39], 0, v[0:1]
	s_mov_b32 m0, s18
	v_lshl_add_u64 v[216:217], s[38:39], 0, v[204:205]
	global_load_lds_dwordx4 v[214:215], off
	s_add_i32 m0, s18, 0x2000
	v_lshl_add_u64 v[218:219], s[46:47], 0, v[194:195]
	global_load_lds_dwordx4 v[216:217], off
	s_mov_b32 m0, s92
	v_lshl_add_u64 v[220:221], s[46:47], 0, v[202:203]
	global_load_lds_dwordx4 v[218:219], off
	s_mov_b32 m0, s93
	s_nop 0
	global_load_lds_dwordx4 v[220:221], off
	s_waitcnt vmcnt(8)
	s_waitcnt lgkmcnt(0)
	s_barrier
; #define PG8_STAGE(bufoff, gbase, voff) do { _Pragma("unroll") for (int _i = 0; _i < 2; ++_i) \
;         __builtin_amdgcn_global_load_lds((const unsigned*)((const char*)(gbase) + (voff)[_i]), (PG8_LAS unsigned*)(lds + (bufoff) + ldsw + _i * 8192), 16, 0, 0); } while (0)
; #define PG8_LDA(dst, b, h) do { _Pragma("unroll") for (int m = 0; m < 4; ++m) _Pragma("unroll") for (int k = 0; k < 2; ++k) dst[m][k] = *(const PG8_LAS bf16x8*)(lds + PG8_SA(b, h) + aoff + m * 2048 + k * 1024); } while (0)
; #define PG8_LDB(dst, b, h) do { _Pragma("unroll") for (int n = 0; n < 2; ++n) _Pragma("unroll") for (int k = 0; k < 2; ++k) dst[n][k] = *(const PG8_LAS bf16x8*)(lds + PG8_SB(b, h) + boff + n * 2048 + k * 1024); } while (0)
; #define PG8_MMA(ai, bj, At, Bt) do { __builtin_amdgcn_s_setprio(1); _Pragma("unroll") for (int m = 0; m < 4; ++m) _Pragma("unroll") for (int n = 0; n < 2; ++n) _Pragma("unroll") for (int k = 0; k < 2; ++k) \
;         acc[ai][bj][m][n] = __builtin_amdgcn_mfma_f32_16x16x32_bf16(Bt[n][k], At[m][k], acc[ai][bj][m][n], 0, 0, 0); __builtin_amdgcn_s_setprio(0); } while (0)
; #define PG8_WAIT_V(n) asm volatile("s_waitcnt vmcnt(" #n ")" ::: "memory")
; #define PG8_WAIT_L(n) asm volatile("s_waitcnt lgkmcnt(" #n ")" ::: "memory")
; #define PG8_BAR __builtin_amdgcn_s_barrier()
; #define PG8_SCHED __builtin_amdgcn_sched_barrier(0)
; template <class Epi, class Sched, bool ALIGN_EPI = false, bool SP2 = false>
; __device__ __forceinline__ void gemm_phase(PG8_LAS unsigned char* lds, const Gemm g, const Sched& S, const Epi& E) {
;     ...
;             PG8_WAIT_V(8); PG8_WAIT_L(0); PG8_BAR; PG8_MMA(1, 0, At, B0); PG8_MMA(1, 1, At, B1); PG8_BAR; PG8_SCHED;
;             PG8_LDB(B0, 1, 0); PG8_LDB(B1, 1, 1); PG8_SCHED; PG8_LDA(At, 1, 0); PG8_STAGE(PG8_SA(0, 1), a2 + hstep, voffA);
;             PG8_WAIT_V(8); PG8_WAIT_L(0); PG8_BAR; PG8_MMA(0, 0, At, B0); PG8_MMA(0, 1, At, B1); PG8_BAR; PG8_SCHED;
	s_setprio 1
	v_mfma_f32_16x16x32_bf16 v[62:65], v[110:113], v[162:165], v[62:65]
	v_mfma_f32_16x16x32_bf16 v[62:65], v[118:121], v[166:169], v[62:65]
	v_mfma_f32_16x16x32_bf16 v[46:49], v[110:113], v[170:173], v[46:49]
	v_mfma_f32_16x16x32_bf16 v[46:49], v[118:121], v[174:177], v[46:49]
	v_mfma_f32_16x16x32_bf16 v[30:33], v[110:113], v[178:181], v[30:33]
	v_mfma_f32_16x16x32_bf16 v[30:33], v[118:121], v[182:185], v[30:33]
	v_mfma_f32_16x16x32_bf16 v[14:17], v[110:113], v[186:189], v[14:17]
	v_mfma_f32_16x16x32_bf16 v[14:17], v[118:121], v[190:193], v[14:17]
	v_mfma_f32_16x16x32_bf16 v[58:61], v[138:141], v[162:165], v[58:61]
	v_mfma_f32_16x16x32_bf16 v[58:61], v[142:145], v[166:169], v[58:61]
	v_mfma_f32_16x16x32_bf16 v[42:45], v[138:141], v[170:173], v[42:45]
	v_mfma_f32_16x16x32_bf16 v[42:45], v[142:145], v[174:177], v[42:45]
	v_mfma_f32_16x16x32_bf16 v[26:29], v[138:141], v[178:181], v[26:29]
	v_mfma_f32_16x16x32_bf16 v[26:29], v[142:145], v[182:185], v[26:29]
	v_mfma_f32_16x16x32_bf16 v[10:13], v[138:141], v[186:189], v[10:13]
	v_mfma_f32_16x16x32_bf16 v[10:13], v[142:145], v[190:193], v[10:13]
	v_mfma_f32_16x16x32_bf16 v[54:57], v[146:149], v[162:165], v[54:57]
	v_mfma_f32_16x16x32_bf16 v[54:57], v[150:153], v[166:169], v[54:57]
	v_mfma_f32_16x16x32_bf16 v[38:41], v[146:149], v[170:173], v[38:41]
	v_mfma_f32_16x16x32_bf16 v[38:41], v[150:153], v[174:177], v[38:41]
	v_mfma_f32_16x16x32_bf16 v[22:25], v[146:149], v[178:181], v[22:25]
	v_mfma_f32_16x16x32_bf16 v[22:25], v[150:153], v[182:185], v[22:25]
	v_mfma_f32_16x16x32_bf16 v[6:9], v[146:149], v[186:189], v[6:9]
	v_mfma_f32_16x16x32_bf16 v[6:9], v[150:153], v[190:193], v[6:9]
	v_mfma_f32_16x16x32_bf16 v[50:53], v[154:157], v[162:165], v[50:53]
	v_mfma_f32_16x16x32_bf16 v[50:53], v[158:161], v[166:169], v[50:53]
	v_mfma_f32_16x16x32_bf16 v[34:37], v[154:157], v[170:173], v[34:37]
	v_mfma_f32_16x16x32_bf16 v[34:37], v[158:161], v[174:177], v[34:37]
	v_mfma_f32_16x16x32_bf16 v[18:21], v[154:157], v[178:181], v[18:21]
	v_mfma_f32_16x16x32_bf16 v[18:21], v[158:161], v[182:185], v[18:21]
	v_mfma_f32_16x16x32_bf16 v[2:5], v[154:157], v[186:189], v[2:5]
	v_mfma_f32_16x16x32_bf16 v[2:5], v[158:161], v[190:193], v[2:5]
	s_setprio 0
	s_barrier
	s_add_i32 s18, 0, 0x18000
	s_add_i32 vcc_hi, 0, 0x1c000
	v_add_u32_e32 v142, s18, v245
	v_add_u32_e32 v158, vcc_hi, v245
	ds_read_b128 v[110:113], v142
	ds_read_b128 v[118:121], v142 offset:1024
	ds_read_b128 v[138:141], v142 offset:2048
	ds_read_b128 v[142:145], v142 offset:3072
	ds_read_b128 v[146:149], v158
	ds_read_b128 v[150:153], v158 offset:1024
	ds_read_b128 v[154:157], v158 offset:2048
	ds_read_b128 v[158:161], v158 offset:3072
	s_add_u32 s38, s46, s58
	s_addc_u32 s39, s47, 0
	s_mov_b32 m0, s94
	v_lshl_add_u64 v[222:223], s[38:39], 0, v[194:195]
	ds_read_b128 v[162:165], v247 offset:32768
	ds_read_b128 v[166:169], v247 offset:33792
	ds_read_b128 v[170:173], v247 offset:34816
	ds_read_b128 v[174:177], v247 offset:35840
	ds_read_b128 v[178:181], v247 offset:36864
	ds_read_b128 v[182:185], v247 offset:37888
	ds_read_b128 v[186:189], v247 offset:38912
	ds_read_b128 v[190:193], v247 offset:39936
	global_load_lds_dwordx4 v[222:223], off
	v_lshl_add_u64 v[222:223], s[38:39], 0, v[202:203]
	s_mov_b32 m0, s95
	s_nop 0
	global_load_lds_dwordx4 v[222:223], off
	s_waitcnt vmcnt(8)
	s_waitcnt lgkmcnt(0)
	s_barrier
	s_setprio 1
	v_mfma_f32_16x16x32_bf16 v[130:133], v[110:113], v[162:165], v[130:133]
	v_mfma_f32_16x16x32_bf16 v[130:133], v[118:121], v[166:169], v[130:133]
	v_mfma_f32_16x16x32_bf16 v[114:117], v[110:113], v[170:173], v[114:117]
	v_mfma_f32_16x16x32_bf16 v[114:117], v[118:121], v[174:177], v[114:117]
	v_mfma_f32_16x16x32_bf16 v[94:97], v[110:113], v[178:181], v[94:97]
	v_mfma_f32_16x16x32_bf16 v[94:97], v[118:121], v[182:185], v[94:97]
	v_mfma_f32_16x16x32_bf16 v[78:81], v[110:113], v[186:189], v[78:81]
	v_mfma_f32_16x16x32_bf16 v[78:81], v[118:121], v[190:193], v[78:81]
	v_mfma_f32_16x16x32_bf16 v[134:137], v[138:141], v[162:165], v[134:137]
	v_mfma_f32_16x16x32_bf16 v[134:137], v[142:145], v[166:169], v[134:137]
	v_mfma_f32_16x16x32_bf16 v[106:109], v[138:141], v[170:173], v[106:109]
	v_mfma_f32_16x16x32_bf16 v[106:109], v[142:145], v[174:177], v[106:109]
	v_mfma_f32_16x16x32_bf16 v[90:93], v[138:141], v[178:181], v[90:93]
	v_mfma_f32_16x16x32_bf16 v[90:93], v[142:145], v[182:185], v[90:93]
	v_mfma_f32_16x16x32_bf16 v[74:77], v[138:141], v[186:189], v[74:77]
	v_mfma_f32_16x16x32_bf16 v[74:77], v[142:145], v[190:193], v[74:77]
	v_mfma_f32_16x16x32_bf16 v[126:129], v[146:149], v[162:165], v[126:129]
	v_mfma_f32_16x16x32_bf16 v[126:129], v[150:153], v[166:169], v[126:129]
	v_mfma_f32_16x16x32_bf16 v[102:105], v[146:149], v[170:173], v[102:105]
	v_mfma_f32_16x16x32_bf16 v[102:105], v[150:153], v[174:177], v[102:105]
	v_mfma_f32_16x16x32_bf16 v[86:89], v[146:149], v[178:181], v[86:89]
	v_mfma_f32_16x16x32_bf16 v[86:89], v[150:153], v[182:185], v[86:89]
	v_mfma_f32_16x16x32_bf16 v[70:73], v[146:149], v[186:189], v[70:73]
	v_mfma_f32_16x16x32_bf16 v[70:73], v[150:153], v[190:193], v[70:73]
	v_mfma_f32_16x16x32_bf16 v[122:125], v[154:157], v[162:165], v[122:125]
	v_mfma_f32_16x16x32_bf16 v[122:125], v[158:161], v[166:169], v[122:125]
	v_mfma_f32_16x16x32_bf16 v[98:101], v[154:157], v[170:173], v[98:101]
	v_mfma_f32_16x16x32_bf16 v[98:101], v[158:161], v[174:177], v[98:101]
	v_mfma_f32_16x16x32_bf16 v[82:85], v[154:157], v[178:181], v[82:85]
	v_mfma_f32_16x16x32_bf16 v[82:85], v[158:161], v[182:185], v[82:85]
	v_mfma_f32_16x16x32_bf16 v[66:69], v[154:157], v[186:189], v[66:69]
	v_mfma_f32_16x16x32_bf16 v[66:69], v[158:161], v[190:193], v[66:69]
	s_setprio 0
	s_barrier
; #define PG8_STAGE(bufoff, gbase, voff) do { _Pragma("unroll") for (int _i = 0; _i < 2; ++_i) \
;         __builtin_amdgcn_global_load_lds((const unsigned*)((const char*)(gbase) + (voff)[_i]), (PG8_LAS unsigned*)(lds + (bufoff) + ldsw + _i * 8192), 16, 0, 0); } while (0)
; #define PG8_LDA(dst, b, h) do { _Pragma("unroll") for (int m = 0; m < 4; ++m) _Pragma("unroll") for (int k = 0; k < 2; ++k) dst[m][k] = *(const PG8_LAS bf16x8*)(lds + PG8_SA(b, h) + aoff + m * 2048 + k * 1024); } while (0)
; #define PG8_WAIT_V(n) asm volatile("s_waitcnt vmcnt(" #n ")" ::: "memory")
; template <class Epi, class Sched, bool ALIGN_EPI = false, bool SP2 = false>
; __device__ __forceinline__ void gemm_phase(PG8_LAS unsigned char* lds, const Gemm g, const Sched& S, const Epi& E) {
;     ...
;             PG8_LDA(At, 1, 1); PG8_STAGE(PG8_SB(1, 0), b3, voffB); PG8_STAGE(PG8_SB(1, 1), b3 + hstep, voffB); PG8_STAGE(PG8_SA(1, 0), a3, voffA);
;             PG8_WAIT_V(8); PG8_WAIT_L(0); PG8_BAR; PG8_MMA(1, 0, At, B0); PG8_MMA(1, 1, At, B1); PG8_BAR; PG8_SCHED;
;             } else {
;             PG8_LDB(B0, 0, 0); PG8_SCHED; PG8_LDA(At, 0, 0); PG8_STAGE(PG8_SA(1, 1), a1 + hstep, voffA);
;             PG8_WAIT_L(8); PG8_BAR; PG8_WAIT_L(0); PG8_MMA(0, 0, At, B0); PG8_BAR; PG8_SCHED;
;             PG8_LDB(B1, 0, 1); PG8_STAGE(PG8_SB(0, 0), b2, voffB);
;             PG8_BAR; PG8_WAIT_L(0); PG8_MMA(0, 1, At, B1); PG8_BAR;
;             PG8_LDA(At, 0, 1); PG8_STAGE(PG8_SA(0, 0), a2, voffA);
;             PG8_BAR; PG8_WAIT_L(0); PG8_MMA(1, 0, At, B0); PG8_BAR; PG8_SCHED;
;             PG8_STAGE(PG8_SB(0, 1), b2 + hstep, voffB);
;             PG8_WAIT_V(6); PG8_BAR; PG8_MMA(1, 1, At, B1); PG8_BAR;
;             PG8_LDB(B0, 1, 0); PG8_SCHED; PG8_LDA(At, 1, 0); PG8_STAGE(PG8_SA(0, 1), a2 + hstep, voffA);
;             PG8_WAIT_L(8); PG8_BAR; PG8_WAIT_L(0); PG8_MMA(0, 0, At, B0); PG8_BAR; PG8_SCHED;
;             PG8_LDB(B1, 1, 1); PG8_STAGE(PG8_SB(1, 0), b3, voffB);
;             PG8_BAR; PG8_WAIT_L(0); PG8_MMA(0, 1, At, B1); PG8_BAR;
;             PG8_LDA(At, 1, 1); PG8_STAGE(PG8_SA(1, 0), a3, voffA);
;             PG8_BAR; PG8_WAIT_L(0); PG8_MMA(1, 0, At, B0); PG8_BAR; PG8_SCHED;
;             PG8_STAGE(PG8_SB(1, 1), b3 + hstep, voffB);
;             PG8_WAIT_V(6); PG8_BAR; PG8_MMA(1, 1, At, B1); PG8_BAR;
;             }
;         }
;         if constexpr (ALIGN_EPI) { if (wr == 0) PG8_BAR; }
	s_add_i32 s18, s18, s6
	v_lshl_add_u64 v[210:211], v[210:211], 0, s[30:31]
	s_mov_b32 m0, s18
	ds_read_b128 v[162:165], v247 offset:49152
	ds_read_b128 v[166:169], v247 offset:50176
	ds_read_b128 v[170:173], v247 offset:51200
	ds_read_b128 v[174:177], v247 offset:52224
	ds_read_b128 v[178:181], v247 offset:53248
	ds_read_b128 v[182:185], v247 offset:54272
	ds_read_b128 v[186:189], v247 offset:55296
	ds_read_b128 v[190:193], v247 offset:56320
	global_load_lds_dwordx4 v[210:211], off
	v_lshl_add_u64 v[210:211], v[212:213], 0, s[30:31]
	s_add_i32 m0, s18, 0x2000
	s_add_i32 s18, vcc_hi, s6
	global_load_lds_dwordx4 v[210:211], off
	v_lshl_add_u64 v[210:211], v[214:215], 0, s[30:31]
	s_mov_b32 m0, s18
	s_nop 0
	global_load_lds_dwordx4 v[210:211], off
	v_lshl_add_u64 v[210:211], v[216:217], 0, s[30:31]
	s_add_i32 m0, s18, 0x2000
	s_nop 0
	global_load_lds_dwordx4 v[210:211], off
	v_lshl_add_u64 v[210:211], v[218:219], 0, s[30:31]
	s_mov_b32 m0, s97
	s_nop 0
	global_load_lds_dwordx4 v[210:211], off
	v_lshl_add_u64 v[210:211], v[220:221], 0, s[30:31]
	s_mov_b32 m0, s98
	s_nop 0
	global_load_lds_dwordx4 v[210:211], off
	s_waitcnt vmcnt(8)
	s_waitcnt lgkmcnt(0)
	s_barrier
	s_setprio 1
	v_mfma_f32_16x16x32_bf16 v[62:65], v[110:113], v[162:165], v[62:65]
	v_mfma_f32_16x16x32_bf16 v[62:65], v[118:121], v[166:169], v[62:65]
	v_mfma_f32_16x16x32_bf16 v[46:49], v[110:113], v[170:173], v[46:49]
	v_mfma_f32_16x16x32_bf16 v[46:49], v[118:121], v[174:177], v[46:49]
	v_mfma_f32_16x16x32_bf16 v[30:33], v[110:113], v[178:181], v[30:33]
	v_mfma_f32_16x16x32_bf16 v[30:33], v[118:121], v[182:185], v[30:33]
	v_mfma_f32_16x16x32_bf16 v[14:17], v[110:113], v[186:189], v[14:17]
	v_mfma_f32_16x16x32_bf16 v[14:17], v[118:121], v[190:193], v[14:17]
	v_mfma_f32_16x16x32_bf16 v[58:61], v[138:141], v[162:165], v[58:61]
	v_mfma_f32_16x16x32_bf16 v[58:61], v[142:145], v[166:169], v[58:61]
	v_mfma_f32_16x16x32_bf16 v[42:45], v[138:141], v[170:173], v[42:45]
	v_mfma_f32_16x16x32_bf16 v[42:45], v[142:145], v[174:177], v[42:45]
	v_mfma_f32_16x16x32_bf16 v[26:29], v[138:141], v[178:181], v[26:29]
	v_mfma_f32_16x16x32_bf16 v[26:29], v[142:145], v[182:185], v[26:29]
	v_mfma_f32_16x16x32_bf16 v[10:13], v[138:141], v[186:189], v[10:13]
	v_mfma_f32_16x16x32_bf16 v[10:13], v[142:145], v[190:193], v[10:13]
	v_mfma_f32_16x16x32_bf16 v[54:57], v[146:149], v[162:165], v[54:57]
	v_mfma_f32_16x16x32_bf16 v[54:57], v[150:153], v[166:169], v[54:57]
	v_mfma_f32_16x16x32_bf16 v[38:41], v[146:149], v[170:173], v[38:41]
	v_mfma_f32_16x16x32_bf16 v[38:41], v[150:153], v[174:177], v[38:41]
	v_mfma_f32_16x16x32_bf16 v[22:25], v[146:149], v[178:181], v[22:25]
	v_mfma_f32_16x16x32_bf16 v[22:25], v[150:153], v[182:185], v[22:25]
	v_mfma_f32_16x16x32_bf16 v[6:9], v[146:149], v[186:189], v[6:9]
	v_mfma_f32_16x16x32_bf16 v[6:9], v[150:153], v[190:193], v[6:9]
	v_mfma_f32_16x16x32_bf16 v[50:53], v[154:157], v[162:165], v[50:53]
	v_mfma_f32_16x16x32_bf16 v[50:53], v[158:161], v[166:169], v[50:53]
	v_mfma_f32_16x16x32_bf16 v[34:37], v[154:157], v[170:173], v[34:37]
	v_mfma_f32_16x16x32_bf16 v[34:37], v[158:161], v[174:177], v[34:37]
	v_mfma_f32_16x16x32_bf16 v[18:21], v[154:157], v[178:181], v[18:21]
	v_mfma_f32_16x16x32_bf16 v[18:21], v[158:161], v[182:185], v[18:21]
	v_mfma_f32_16x16x32_bf16 v[2:5], v[154:157], v[186:189], v[2:5]
	v_mfma_f32_16x16x32_bf16 v[2:5], v[158:161], v[190:193], v[2:5]
	s_setprio 0
	s_barrier
	s_add_u32 s48, s48, 0x100
	s_addc_u32 s49, s49, 0
	s_add_u32 s50, s50, 0x100
	s_addc_u32 s51, s51, 0
	s_cmp_ge_u32 vcc_lo, s96
	s_mov_b32 s46, vcc_lo
	s_cbranch_scc0 .LBB0_274
	s_and_b64 vcc, exec, s[72:73]
	s_cbranch_vccz .LBB0_277
	s_barrier

; #define PG8_STAGE(bufoff, gbase, voff) do { _Pragma("unroll") for (int _i = 0; _i < 2; ++_i) \
;         __builtin_amdgcn_global_load_lds((const unsigned*)((const char*)(gbase) + (voff)[_i]), (PG8_LAS unsigned*)(lds + (bufoff) + ldsw + _i * 8192), 16, 0, 0); } while (0)
; #define PG8_LDA(dst, b, h) do { _Pragma("unroll") for (int m = 0; m < 4; ++m) _Pragma("unroll") for (int k = 0; k < 2; ++k) dst[m][k] = *(const PG8_LAS bf16x8*)(lds + PG8_SA(b, h) + aoff + m * 2048 + k * 1024); } while (0)
; #define PG8_LDB(dst, b, h) do { _Pragma("unroll") for (int n = 0; n < 2; ++n) _Pragma("unroll") for (int k = 0; k < 2; ++k) dst[n][k] = *(const PG8_LAS bf16x8*)(lds + PG8_SB(b, h) + boff + n * 2048 + k * 1024); } while (0)
; #define PG8_WAIT_V(n) asm volatile("s_waitcnt vmcnt(" #n ")" ::: "memory")
; #define PG8_WAIT_L(n) asm volatile("s_waitcnt lgkmcnt(" #n ")" ::: "memory")
; #define PG8_BAR __builtin_amdgcn_s_barrier()
; #define PG8_SCHED __builtin_amdgcn_sched_barrier(0)
; template <class Epi, class Sched, bool ALIGN_EPI = false, bool SP2 = false>
; __device__ __forceinline__ void gemm_phase(PG8_LAS unsigned char* lds, const Gemm g, const Sched& S, const Epi& E) {
;     ...
;         const bool has_next = S.next(ui + 1, nxt);
;         const char* nA = has_next ? (const char*)g.A + (size_t)nxt.pm * tstep : cA; const char* nB = has_next ? (const char*)g.Bt + (size_t)nxt.pn * tstep : cB;
;         for (int t = 0; t < nt; t += 2) {
;             const bool last = (t == nt - 2);
;             const char* a1 = cA + (size_t)(t + 1) * kstep;
;             const char* a2 = last ? nA : cA + (size_t)(t + 2) * kstep; const char* b2 = last ? nB : cB + (size_t)(t + 2) * kstep;
;             const char* a3 = a2 + kstep; const char* b3 = b2 + kstep;
;             if (last && has_next) S.a_ready(nxt);
;             if constexpr (SP2) {
;             PG8_LDB(B0, 0, 0); PG8_LDB(B1, 0, 1); PG8_SCHED; PG8_LDA(At, 0, 0); PG8_STAGE(PG8_SA(1, 1), a1 + hstep, voffA);
;             PG8_WAIT_V(8); PG8_WAIT_L(0); PG8_BAR; PG8_MMA(0, 0, At, B0); PG8_MMA(0, 1, At, B1); PG8_BAR; PG8_SCHED;
;             PG8_LDA(At, 0, 1); PG8_STAGE(PG8_SB(0, 0), b2, voffB); PG8_STAGE(PG8_SB(0, 1), b2 + hstep, voffB); PG8_STAGE(PG8_SA(0, 0), a2, voffA);
;             PG8_WAIT_V(8); PG8_WAIT_L(0); PG8_BAR; PG8_MMA(1, 0, At, B0); PG8_MMA(1, 1, At, B1); PG8_BAR; PG8_SCHED;
.LBB0_408:
	s_add_u32 s38, s48, 0xfffc0080
	s_addc_u32 s39, s49, -1
	s_add_i32 s85, 0, 0x10000
	s_cmp_eq_u32 s84, 12
	s_cselect_b32 s73, s21, s39
	s_cselect_b32 s72, s27, s38
	v_add_u32_e32 v0, s85, v167
	s_cselect_b32 s47, s29, s69
	s_cselect_b32 s46, s33, s53
	s_add_i32 s38, 0, 0x14000
	ds_read_b128 v[142:145], v0
	ds_read_b128 v[146:149], v0 offset:1024
	ds_read_b128 v[150:153], v0 offset:2048
	ds_read_b128 v[154:157], v0 offset:3072
	v_add_u32_e32 v0, s38, v167
	ds_read_b128 v[158:161], v0
	ds_read_b128 v[162:165], v0 offset:1024
	ds_read_b128 v[172:175], v0 offset:2048
	ds_read_b128 v[176:179], v0 offset:3072
	v_lshl_add_u64 v[218:219], s[48:49], 0, v[138:139]
	s_add_i32 m0, s76, 0xc000
	ds_read_b128 v[180:183], v170
	ds_read_b128 v[184:187], v170 offset:1024
	ds_read_b128 v[188:191], v170 offset:2048
	ds_read_b128 v[192:195], v170 offset:3072
	ds_read_b128 v[202:205], v170 offset:4096
	ds_read_b128 v[206:209], v170 offset:5120
	ds_read_b128 v[210:213], v170 offset:6144
	ds_read_b128 v[214:217], v170 offset:7168
	global_load_lds_dwordx4 v[218:219], off
	v_lshl_add_u64 v[218:219], s[48:49], 0, v[140:141]
	s_add_i32 m0, s76, 0xe000
	s_nop 0
	global_load_lds_dwordx4 v[218:219], off
	s_waitcnt vmcnt(8)
	s_waitcnt lgkmcnt(0)
	s_barrier
	s_setprio 1
	v_mfma_f32_16x16x32_bf16 v[122:125], v[142:145], v[180:183], v[122:125]
	v_mfma_f32_16x16x32_bf16 v[122:125], v[146:149], v[184:187], v[122:125]
	v_mfma_f32_16x16x32_bf16 v[106:109], v[142:145], v[188:191], v[106:109]
	v_mfma_f32_16x16x32_bf16 v[106:109], v[146:149], v[192:195], v[106:109]
	v_mfma_f32_16x16x32_bf16 v[90:93], v[142:145], v[202:205], v[90:93]
	v_mfma_f32_16x16x32_bf16 v[90:93], v[146:149], v[206:209], v[90:93]
	v_mfma_f32_16x16x32_bf16 v[74:77], v[142:145], v[210:213], v[74:77]
	v_mfma_f32_16x16x32_bf16 v[74:77], v[146:149], v[214:217], v[74:77]
	v_mfma_f32_16x16x32_bf16 v[126:129], v[150:153], v[180:183], v[126:129]
	v_mfma_f32_16x16x32_bf16 v[126:129], v[154:157], v[184:187], v[126:129]
	v_mfma_f32_16x16x32_bf16 v[110:113], v[150:153], v[188:191], v[110:113]
	v_mfma_f32_16x16x32_bf16 v[110:113], v[154:157], v[192:195], v[110:113]
	v_mfma_f32_16x16x32_bf16 v[94:97], v[150:153], v[202:205], v[94:97]
	v_mfma_f32_16x16x32_bf16 v[94:97], v[154:157], v[206:209], v[94:97]
	v_mfma_f32_16x16x32_bf16 v[78:81], v[150:153], v[210:213], v[78:81]
	v_mfma_f32_16x16x32_bf16 v[78:81], v[154:157], v[214:217], v[78:81]
	v_mfma_f32_16x16x32_bf16 v[114:117], v[158:161], v[180:183], v[114:117]
	v_mfma_f32_16x16x32_bf16 v[114:117], v[162:165], v[184:187], v[114:117]
	v_mfma_f32_16x16x32_bf16 v[98:101], v[158:161], v[188:191], v[98:101]
	v_mfma_f32_16x16x32_bf16 v[98:101], v[162:165], v[192:195], v[98:101]
	v_mfma_f32_16x16x32_bf16 v[82:85], v[158:161], v[202:205], v[82:85]
	v_mfma_f32_16x16x32_bf16 v[82:85], v[162:165], v[206:209], v[82:85]
	v_mfma_f32_16x16x32_bf16 v[66:69], v[158:161], v[210:213], v[66:69]
	v_mfma_f32_16x16x32_bf16 v[66:69], v[162:165], v[214:217], v[66:69]
	v_mfma_f32_16x16x32_bf16 v[118:121], v[172:175], v[180:183], v[118:121]
	v_mfma_f32_16x16x32_bf16 v[118:121], v[176:179], v[184:187], v[118:121]
	v_mfma_f32_16x16x32_bf16 v[102:105], v[172:175], v[188:191], v[102:105]
	v_mfma_f32_16x16x32_bf16 v[102:105], v[176:179], v[192:195], v[102:105]
	v_mfma_f32_16x16x32_bf16 v[86:89], v[172:175], v[202:205], v[86:89]
	v_mfma_f32_16x16x32_bf16 v[86:89], v[176:179], v[206:209], v[86:89]
	v_mfma_f32_16x16x32_bf16 v[70:73], v[172:175], v[210:213], v[70:73]
	v_mfma_f32_16x16x32_bf16 v[70:73], v[176:179], v[214:217], v[70:73]
	s_setprio 0
	s_barrier
	s_add_i32 s39, s85, s75
	v_lshl_add_u64 v[218:219], s[46:47], 0, v[134:135]
	s_mov_b32 m0, s39
	ds_read_b128 v[180:183], v170 offset:16384
	ds_read_b128 v[184:187], v170 offset:17408
	ds_read_b128 v[188:191], v170 offset:18432
	ds_read_b128 v[192:195], v170 offset:19456
	ds_read_b128 v[202:205], v170 offset:20480
	ds_read_b128 v[206:209], v170 offset:21504
	ds_read_b128 v[210:213], v170 offset:22528
	ds_read_b128 v[214:217], v170 offset:23552
	global_load_lds_dwordx4 v[218:219], off
	s_add_i32 m0, s39, 0x2000
	s_add_u32 s92, s46, 0x40000
	v_lshl_add_u64 v[220:221], s[46:47], 0, v[130:131]
	s_addc_u32 s93, s47, 0
	s_add_i32 s38, s38, s75
	global_load_lds_dwordx4 v[220:221], off
	v_lshl_add_u64 v[222:223], s[92:93], 0, v[134:135]
	s_mov_b32 m0, s38
	v_lshl_add_u64 v[224:225], s[72:73], 0, v[132:133]
	global_load_lds_dwordx4 v[222:223], off
	v_lshl_add_u64 v[222:223], s[92:93], 0, v[130:131]
	s_add_i32 m0, s38, 0x2000
	s_nop 0
	global_load_lds_dwordx4 v[222:223], off
	v_lshl_add_u64 v[222:223], s[72:73], 0, v[136:137]
	s_mov_b32 m0, s76
	s_nop 0
	global_load_lds_dwordx4 v[222:223], off
	s_mov_b32 m0, s77
	s_nop 0
	global_load_lds_dwordx4 v[224:225], off
	s_waitcnt vmcnt(8)
	s_waitcnt lgkmcnt(0)
	s_barrier
; #define PG8_STAGE(bufoff, gbase, voff) do { _Pragma("unroll") for (int _i = 0; _i < 2; ++_i) \
;         __builtin_amdgcn_global_load_lds((const unsigned*)((const char*)(gbase) + (voff)[_i]), (PG8_LAS unsigned*)(lds + (bufoff) + ldsw + _i * 8192), 16, 0, 0); } while (0)
; #define PG8_LDA(dst, b, h) do { _Pragma("unroll") for (int m = 0; m < 4; ++m) _Pragma("unroll") for (int k = 0; k < 2; ++k) dst[m][k] = *(const PG8_LAS bf16x8*)(lds + PG8_SA(b, h) + aoff + m * 2048 + k * 1024); } while (0)
; #define PG8_LDB(dst, b, h) do { _Pragma("unroll") for (int n = 0; n < 2; ++n) _Pragma("unroll") for (int k = 0; k < 2; ++k) dst[n][k] = *(const PG8_LAS bf16x8*)(lds + PG8_SB(b, h) + boff + n * 2048 + k * 1024); } while (0)
; #define PG8_MMA(ai, bj, At, Bt) do { __builtin_amdgcn_s_setprio(1); _Pragma("unroll") for (int m = 0; m < 4; ++m) _Pragma("unroll") for (int n = 0; n < 2; ++n) _Pragma("unroll") for (int k = 0; k < 2; ++k) \
;         acc[ai][bj][m][n] = __builtin_amdgcn_mfma_f32_16x16x32_bf16(Bt[n][k], At[m][k], acc[ai][bj][m][n], 0, 0, 0); __builtin_amdgcn_s_setprio(0); } while (0)
; #define PG8_WAIT_V(n) asm volatile("s_waitcnt vmcnt(" #n ")" ::: "memory")
; #define PG8_WAIT_L(n) asm volatile("s_waitcnt lgkmcnt(" #n ")" ::: "memory")
; #define PG8_BAR __builtin_amdgcn_s_barrier()
; #define PG8_SCHED __builtin_amdgcn_sched_barrier(0)
; template <class Epi, class Sched, bool ALIGN_EPI = false, bool SP2 = false>
; __device__ __forceinline__ void gemm_phase(PG8_LAS unsigned char* lds, const Gemm g, const Sched& S, const Epi& E) {
;     ...
;             PG8_WAIT_V(8); PG8_WAIT_L(0); PG8_BAR; PG8_MMA(1, 0, At, B0); PG8_MMA(1, 1, At, B1); PG8_BAR; PG8_SCHED;
;             PG8_LDB(B0, 1, 0); PG8_LDB(B1, 1, 1); PG8_SCHED; PG8_LDA(At, 1, 0); PG8_STAGE(PG8_SA(0, 1), a2 + hstep, voffA);
;             PG8_WAIT_V(8); PG8_WAIT_L(0); PG8_BAR; PG8_MMA(0, 0, At, B0); PG8_MMA(0, 1, At, B1); PG8_BAR; PG8_SCHED;
	s_setprio 1
	v_mfma_f32_16x16x32_bf16 v[58:61], v[142:145], v[180:183], v[58:61]
	v_mfma_f32_16x16x32_bf16 v[58:61], v[146:149], v[184:187], v[58:61]
	v_mfma_f32_16x16x32_bf16 v[42:45], v[142:145], v[188:191], v[42:45]
	v_mfma_f32_16x16x32_bf16 v[42:45], v[146:149], v[192:195], v[42:45]
	v_mfma_f32_16x16x32_bf16 v[26:29], v[142:145], v[202:205], v[26:29]
	v_mfma_f32_16x16x32_bf16 v[26:29], v[146:149], v[206:209], v[26:29]
	v_mfma_f32_16x16x32_bf16 v[10:13], v[142:145], v[210:213], v[10:13]
	v_mfma_f32_16x16x32_bf16 v[10:13], v[146:149], v[214:217], v[10:13]
	v_mfma_f32_16x16x32_bf16 v[62:65], v[150:153], v[180:183], v[62:65]
	v_mfma_f32_16x16x32_bf16 v[62:65], v[154:157], v[184:187], v[62:65]
	v_mfma_f32_16x16x32_bf16 v[46:49], v[150:153], v[188:191], v[46:49]
	v_mfma_f32_16x16x32_bf16 v[46:49], v[154:157], v[192:195], v[46:49]
	v_mfma_f32_16x16x32_bf16 v[30:33], v[150:153], v[202:205], v[30:33]
	v_mfma_f32_16x16x32_bf16 v[30:33], v[154:157], v[206:209], v[30:33]
	v_mfma_f32_16x16x32_bf16 v[14:17], v[150:153], v[210:213], v[14:17]
	v_mfma_f32_16x16x32_bf16 v[14:17], v[154:157], v[214:217], v[14:17]
	v_mfma_f32_16x16x32_bf16 v[50:53], v[158:161], v[180:183], v[50:53]
	v_mfma_f32_16x16x32_bf16 v[50:53], v[162:165], v[184:187], v[50:53]
	v_mfma_f32_16x16x32_bf16 v[34:37], v[158:161], v[188:191], v[34:37]
	v_mfma_f32_16x16x32_bf16 v[34:37], v[162:165], v[192:195], v[34:37]
	v_mfma_f32_16x16x32_bf16 v[18:21], v[158:161], v[202:205], v[18:21]
	v_mfma_f32_16x16x32_bf16 v[18:21], v[162:165], v[206:209], v[18:21]
	v_mfma_f32_16x16x32_bf16 v[2:5], v[158:161], v[210:213], v[2:5]
	v_mfma_f32_16x16x32_bf16 v[2:5], v[162:165], v[214:217], v[2:5]
	v_mfma_f32_16x16x32_bf16 v[54:57], v[172:175], v[180:183], v[54:57]
	v_mfma_f32_16x16x32_bf16 v[54:57], v[176:179], v[184:187], v[54:57]
	v_mfma_f32_16x16x32_bf16 v[38:41], v[172:175], v[188:191], v[38:41]
	v_mfma_f32_16x16x32_bf16 v[38:41], v[176:179], v[192:195], v[38:41]
	v_mfma_f32_16x16x32_bf16 v[22:25], v[172:175], v[202:205], v[22:25]
	v_mfma_f32_16x16x32_bf16 v[22:25], v[176:179], v[206:209], v[22:25]
	v_mfma_f32_16x16x32_bf16 v[6:9], v[172:175], v[210:213], v[6:9]
	v_mfma_f32_16x16x32_bf16 v[6:9], v[176:179], v[214:217], v[6:9]
	s_setprio 0
	s_barrier
	s_add_i32 s38, 0, 0x18000
	v_add_u32_e32 v0, s38, v167
	s_add_i32 s39, 0, 0x1c000
	ds_read_b128 v[142:145], v0
	ds_read_b128 v[146:149], v0 offset:1024
	ds_read_b128 v[150:153], v0 offset:2048
	ds_read_b128 v[154:157], v0 offset:3072
	v_add_u32_e32 v0, s39, v167
	ds_read_b128 v[158:161], v0
	ds_read_b128 v[162:165], v0 offset:1024
	ds_read_b128 v[172:175], v0 offset:2048
	ds_read_b128 v[176:179], v0 offset:3072
	s_add_u32 s72, s72, 0x40000
	s_addc_u32 s73, s73, 0
	s_mov_b32 m0, s78
	v_lshl_add_u64 v[226:227], s[72:73], 0, v[136:137]
	ds_read_b128 v[180:183], v170 offset:32768
	ds_read_b128 v[184:187], v170 offset:33792
	ds_read_b128 v[188:191], v170 offset:34816
	ds_read_b128 v[192:195], v170 offset:35840
	ds_read_b128 v[202:205], v170 offset:36864
	ds_read_b128 v[206:209], v170 offset:37888
	ds_read_b128 v[210:213], v170 offset:38912
	ds_read_b128 v[214:217], v170 offset:39936
	global_load_lds_dwordx4 v[226:227], off
	v_lshl_add_u64 v[226:227], s[72:73], 0, v[132:133]
	s_mov_b32 m0, s79
	s_nop 0
	global_load_lds_dwordx4 v[226:227], off
	s_waitcnt vmcnt(8)
	s_waitcnt lgkmcnt(0)
	s_barrier
	s_setprio 1
	v_mfma_f32_16x16x32_bf16 v[122:125], v[142:145], v[180:183], v[122:125]
	v_mfma_f32_16x16x32_bf16 v[122:125], v[146:149], v[184:187], v[122:125]
	v_mfma_f32_16x16x32_bf16 v[106:109], v[142:145], v[188:191], v[106:109]
	v_mfma_f32_16x16x32_bf16 v[106:109], v[146:149], v[192:195], v[106:109]
	v_mfma_f32_16x16x32_bf16 v[90:93], v[142:145], v[202:205], v[90:93]
	v_mfma_f32_16x16x32_bf16 v[90:93], v[146:149], v[206:209], v[90:93]
	v_mfma_f32_16x16x32_bf16 v[74:77], v[142:145], v[210:213], v[74:77]
	v_mfma_f32_16x16x32_bf16 v[74:77], v[146:149], v[214:217], v[74:77]
	v_mfma_f32_16x16x32_bf16 v[126:129], v[150:153], v[180:183], v[126:129]
	v_mfma_f32_16x16x32_bf16 v[126:129], v[154:157], v[184:187], v[126:129]
	v_mfma_f32_16x16x32_bf16 v[110:113], v[150:153], v[188:191], v[110:113]
	v_mfma_f32_16x16x32_bf16 v[110:113], v[154:157], v[192:195], v[110:113]
	v_mfma_f32_16x16x32_bf16 v[94:97], v[150:153], v[202:205], v[94:97]
	v_mfma_f32_16x16x32_bf16 v[94:97], v[154:157], v[206:209], v[94:97]
	v_mfma_f32_16x16x32_bf16 v[78:81], v[150:153], v[210:213], v[78:81]
	v_mfma_f32_16x16x32_bf16 v[78:81], v[154:157], v[214:217], v[78:81]
	v_mfma_f32_16x16x32_bf16 v[114:117], v[158:161], v[180:183], v[114:117]
	v_mfma_f32_16x16x32_bf16 v[114:117], v[162:165], v[184:187], v[114:117]
	v_mfma_f32_16x16x32_bf16 v[98:101], v[158:161], v[188:191], v[98:101]
	v_mfma_f32_16x16x32_bf16 v[98:101], v[162:165], v[192:195], v[98:101]
	v_mfma_f32_16x16x32_bf16 v[82:85], v[158:161], v[202:205], v[82:85]
	v_mfma_f32_16x16x32_bf16 v[82:85], v[162:165], v[206:209], v[82:85]
	v_mfma_f32_16x16x32_bf16 v[66:69], v[158:161], v[210:213], v[66:69]
	v_mfma_f32_16x16x32_bf16 v[66:69], v[162:165], v[214:217], v[66:69]
	v_mfma_f32_16x16x32_bf16 v[118:121], v[172:175], v[180:183], v[118:121]
	v_mfma_f32_16x16x32_bf16 v[118:121], v[176:179], v[184:187], v[118:121]
	v_mfma_f32_16x16x32_bf16 v[102:105], v[172:175], v[188:191], v[102:105]
	v_mfma_f32_16x16x32_bf16 v[102:105], v[176:179], v[192:195], v[102:105]
	v_mfma_f32_16x16x32_bf16 v[86:89], v[172:175], v[202:205], v[86:89]
	v_mfma_f32_16x16x32_bf16 v[86:89], v[176:179], v[206:209], v[86:89]
	v_mfma_f32_16x16x32_bf16 v[70:73], v[172:175], v[210:213], v[70:73]
	v_mfma_f32_16x16x32_bf16 v[70:73], v[176:179], v[214:217], v[70:73]
	s_setprio 0
	s_barrier
; #define PG8_STAGE(bufoff, gbase, voff) do { _Pragma("unroll") for (int _i = 0; _i < 2; ++_i) \
;         __builtin_amdgcn_global_load_lds((const unsigned*)((const char*)(gbase) + (voff)[_i]), (PG8_LAS unsigned*)(lds + (bufoff) + ldsw + _i * 8192), 16, 0, 0); } while (0)
; #define PG8_LDA(dst, b, h) do { _Pragma("unroll") for (int m = 0; m < 4; ++m) _Pragma("unroll") for (int k = 0; k < 2; ++k) dst[m][k] = *(const PG8_LAS bf16x8*)(lds + PG8_SA(b, h) + aoff + m * 2048 + k * 1024); } while (0)
; #define PG8_WAIT_V(n) asm volatile("s_waitcnt vmcnt(" #n ")" ::: "memory")
; template <class Epi, class Sched, bool ALIGN_EPI = false, bool SP2 = false>
; __device__ __forceinline__ void gemm_phase(PG8_LAS unsigned char* lds, const Gemm g, const Sched& S, const Epi& E) {
;     ...
;             PG8_LDA(At, 1, 1); PG8_STAGE(PG8_SB(1, 0), b3, voffB); PG8_STAGE(PG8_SB(1, 1), b3 + hstep, voffB); PG8_STAGE(PG8_SA(1, 0), a3, voffA);
;             PG8_WAIT_V(8); PG8_WAIT_L(0); PG8_BAR; PG8_MMA(1, 0, At, B0); PG8_MMA(1, 1, At, B1); PG8_BAR; PG8_SCHED;
;             } else {
;             PG8_LDB(B0, 0, 0); PG8_SCHED; PG8_LDA(At, 0, 0); PG8_STAGE(PG8_SA(1, 1), a1 + hstep, voffA);
;             PG8_WAIT_L(8); PG8_BAR; PG8_WAIT_L(0); PG8_MMA(0, 0, At, B0); PG8_BAR; PG8_SCHED;
;             PG8_LDB(B1, 0, 1); PG8_STAGE(PG8_SB(0, 0), b2, voffB);
;             PG8_BAR; PG8_WAIT_L(0); PG8_MMA(0, 1, At, B1); PG8_BAR;
;             PG8_LDA(At, 0, 1); PG8_STAGE(PG8_SA(0, 0), a2, voffA);
;             PG8_BAR; PG8_WAIT_L(0); PG8_MMA(1, 0, At, B0); PG8_BAR; PG8_SCHED;
;             PG8_STAGE(PG8_SB(0, 1), b2 + hstep, voffB);
;             PG8_WAIT_V(6); PG8_BAR; PG8_MMA(1, 1, At, B1); PG8_BAR;
;             PG8_LDB(B0, 1, 0); PG8_SCHED; PG8_LDA(At, 1, 0); PG8_STAGE(PG8_SA(0, 1), a2 + hstep, voffA);
;             PG8_WAIT_L(8); PG8_BAR; PG8_WAIT_L(0); PG8_MMA(0, 0, At, B0); PG8_BAR; PG8_SCHED;
;             PG8_LDB(B1, 1, 1); PG8_STAGE(PG8_SB(1, 0), b3, voffB);
;             PG8_BAR; PG8_WAIT_L(0); PG8_MMA(0, 1, At, B1); PG8_BAR;
;             PG8_LDA(At, 1, 1); PG8_STAGE(PG8_SA(1, 0), a3, voffA);
;             PG8_BAR; PG8_WAIT_L(0); PG8_MMA(1, 0, At, B0); PG8_BAR; PG8_SCHED;
;             PG8_STAGE(PG8_SB(1, 1), b3 + hstep, voffB);
;             PG8_WAIT_V(6); PG8_BAR; PG8_MMA(1, 1, At, B1); PG8_BAR;
;             }
;         }
;         if constexpr (ALIGN_EPI) { if (wr == 0) PG8_BAR; }
	s_add_i32 s38, s38, s75
	v_lshl_add_u64 v[218:219], v[218:219], 0, s[30:31]
	s_mov_b32 m0, s38
	ds_read_b128 v[180:183], v170 offset:49152
	ds_read_b128 v[184:187], v170 offset:50176
	ds_read_b128 v[188:191], v170 offset:51200
	ds_read_b128 v[192:195], v170 offset:52224
	ds_read_b128 v[202:205], v170 offset:53248
	ds_read_b128 v[206:209], v170 offset:54272
	ds_read_b128 v[210:213], v170 offset:55296
	ds_read_b128 v[214:217], v170 offset:56320
	global_load_lds_dwordx4 v[218:219], off
	s_add_i32 m0, s38, 0x2000
	s_add_u32 s46, s46, 0x40080
	v_lshl_add_u64 v[218:219], v[220:221], 0, s[30:31]
	s_addc_u32 s47, s47, 0
	s_add_i32 s38, s39, s75
	global_load_lds_dwordx4 v[218:219], off
	v_lshl_add_u64 v[218:219], s[46:47], 0, v[134:135]
	s_mov_b32 m0, s38
	s_nop 0
	global_load_lds_dwordx4 v[218:219], off
	v_lshl_add_u64 v[218:219], s[46:47], 0, v[130:131]
	s_add_i32 m0, s38, 0x2000
	s_nop 0
	global_load_lds_dwordx4 v[218:219], off
	v_lshl_add_u64 v[218:219], v[222:223], 0, s[30:31]
	s_mov_b32 m0, s80
	s_nop 0
	global_load_lds_dwordx4 v[218:219], off
	v_lshl_add_u64 v[218:219], v[224:225], 0, s[30:31]
	s_mov_b32 m0, s81
	s_nop 0
	global_load_lds_dwordx4 v[218:219], off
	s_waitcnt vmcnt(8)
	s_waitcnt lgkmcnt(0)
	s_barrier
	s_setprio 1
	v_mfma_f32_16x16x32_bf16 v[58:61], v[142:145], v[180:183], v[58:61]
	v_mfma_f32_16x16x32_bf16 v[58:61], v[146:149], v[184:187], v[58:61]
	v_mfma_f32_16x16x32_bf16 v[42:45], v[142:145], v[188:191], v[42:45]
	v_mfma_f32_16x16x32_bf16 v[42:45], v[146:149], v[192:195], v[42:45]
	v_mfma_f32_16x16x32_bf16 v[26:29], v[142:145], v[202:205], v[26:29]
	v_mfma_f32_16x16x32_bf16 v[26:29], v[146:149], v[206:209], v[26:29]
	v_mfma_f32_16x16x32_bf16 v[10:13], v[142:145], v[210:213], v[10:13]
	v_mfma_f32_16x16x32_bf16 v[10:13], v[146:149], v[214:217], v[10:13]
	v_mfma_f32_16x16x32_bf16 v[62:65], v[150:153], v[180:183], v[62:65]
	v_mfma_f32_16x16x32_bf16 v[62:65], v[154:157], v[184:187], v[62:65]
	v_mfma_f32_16x16x32_bf16 v[46:49], v[150:153], v[188:191], v[46:49]
	v_mfma_f32_16x16x32_bf16 v[46:49], v[154:157], v[192:195], v[46:49]
	v_mfma_f32_16x16x32_bf16 v[30:33], v[150:153], v[202:205], v[30:33]
	v_mfma_f32_16x16x32_bf16 v[30:33], v[154:157], v[206:209], v[30:33]
	v_mfma_f32_16x16x32_bf16 v[14:17], v[150:153], v[210:213], v[14:17]
	v_mfma_f32_16x16x32_bf16 v[14:17], v[154:157], v[214:217], v[14:17]
	v_mfma_f32_16x16x32_bf16 v[50:53], v[158:161], v[180:183], v[50:53]
	v_mfma_f32_16x16x32_bf16 v[50:53], v[162:165], v[184:187], v[50:53]
	v_mfma_f32_16x16x32_bf16 v[34:37], v[158:161], v[188:191], v[34:37]
	v_mfma_f32_16x16x32_bf16 v[34:37], v[162:165], v[192:195], v[34:37]
	v_mfma_f32_16x16x32_bf16 v[18:21], v[158:161], v[202:205], v[18:21]
	v_mfma_f32_16x16x32_bf16 v[18:21], v[162:165], v[206:209], v[18:21]
	v_mfma_f32_16x16x32_bf16 v[2:5], v[158:161], v[210:213], v[2:5]
	v_mfma_f32_16x16x32_bf16 v[2:5], v[162:165], v[214:217], v[2:5]
	v_mfma_f32_16x16x32_bf16 v[54:57], v[172:175], v[180:183], v[54:57]
	v_mfma_f32_16x16x32_bf16 v[54:57], v[176:179], v[184:187], v[54:57]
	v_mfma_f32_16x16x32_bf16 v[38:41], v[172:175], v[188:191], v[38:41]
	v_mfma_f32_16x16x32_bf16 v[38:41], v[176:179], v[192:195], v[38:41]
	v_mfma_f32_16x16x32_bf16 v[22:25], v[172:175], v[202:205], v[22:25]
	v_mfma_f32_16x16x32_bf16 v[22:25], v[176:179], v[206:209], v[22:25]
	v_mfma_f32_16x16x32_bf16 v[6:9], v[172:175], v[210:213], v[6:9]
	v_mfma_f32_16x16x32_bf16 v[6:9], v[176:179], v[214:217], v[6:9]
	s_setprio 0
	s_barrier
	s_add_i32 s84, s84, 2
	s_add_u32 s48, s48, 0x100
	s_addc_u32 s49, s49, 0
	s_add_u32 s53, s53, 0x100
	s_addc_u32 s69, s69, 0
	s_cmp_gt_u32 s84, 13
	s_cbranch_scc0 .LBB0_408
	s_and_b64 vcc, exec, s[64:65]
	s_cbranch_vccz .LBB0_411
	s_barrier
